# K-tile-major tiled layout for HB: p8 epilogue stores + p9 A-operand DMA addresses (contiguous 32KB A panels per K-tile)
# baseline (speedup 1.0000x reference)
; __global__ void __launch_bounds__(512, 2) fwd_kernel(Params p) {
;     ...
;         unsigned char* ws = p.ws; asm volatile("" : "+s"(ws));
;         int tid = threadIdx.x; asm volatile("" : "+v"(tid));
;         int bid = blockIdx.x; asm volatile("" : "+s"(bid));
;         int z0 = 0; asm volatile("" : "+s"(z0));
;         bf16_t* Wt_in = (bf16_t*)(ws + WS_WIN); bf16_t* Wt_bra = (bf16_t*)(ws + WS_WBRA); bf16_t* Wt_brb = (bf16_t*)(ws + WS_WBRB); bf16_t* Wt_o = (bf16_t*)(ws + WS_WO);
;         bf16_t* Wt_xq = (bf16_t*)(ws + WS_WXQ); bf16_t* Wt_xkv = (bf16_t*)(ws + WS_WXKV); bf16_t* Wt_xo = (bf16_t*)(ws + WS_WXO); bf16_t* Wt_up = (bf16_t*)(ws + WS_WUP); bf16_t* Wt_dn = (bf16_t*)(ws + WS_WDN);
;         bf16_t* TB = (bf16_t*)(ws + WS_XB);
;         bf16_t* GU = (bf16_t*)(ws + WS_R1 + R1_GU); bf16_t* GV = (bf16_t*)(ws + WS_R1 + R1_GV); bf16_t* QB = (bf16_t*)(ws + WS_R1 + R1_Q); bf16_t* KB = (bf16_t*)(ws + WS_R1 + R1_K);
;         bf16_t* VB = (bf16_t*)(ws + WS_R1 + R1_V); bf16_t* SA = (bf16_t*)(ws + WS_R1 + R1_SA); bf16_t* SB = (bf16_t*)(ws + WS_R1 + R1_SB); bf16_t* HB = (bf16_t*)(ws + WS_R1);
;         bf16_t* MERGED = GU;
;         bf16_t* SGUO = (bf16_t*)(ws + WS_R2); bf16_t* ATTO = (bf16_t*)(ws + WS_R2 + (size_t)M * GW * 2); bf16_t* XQ = SGUO; bf16_t* XO = ATTO;
;         bf16_t* MEMB = (bf16_t*)(ws + WS_MEMB); bf16_t* XKV = (bf16_t*)(ws + WS_XKV); float* ROPE = (float*)(ws + WS_ROPE);
;         float* STATSV = (float*)(ws + WS_STATSV); float* CSB = (float*)(ws + WS_CS);
;         float* X = p.out;
;         const int G = gridDim.x;
;         if (ph == DEPTH * NPH) { ln_final(TB, X, p.in[z0 + 21] + (size_t)(DEPTH - 1) * D, p.in[z0 + 22] + (size_t)(DEPTH - 1) * D, tid, bid); break; }
;         const int l = ph / NPH, k = ph % NPH;
;         float* ST0 = (float*)(ws + WS_STATS) + (size_t)((3 * l + 0) & 1) * M * 64; float* ST1 = (float*)(ws + WS_STATS) + (size_t)((3 * l + 1) & 1) * M * 64;
;         float* ST2 = (float*)(ws + WS_STATS) + (size_t)((3 * l + 2) & 1) * M * 64;
;         const float* STP = ST1;
;         switch (k) {
;     ...
;         case 9: { pg8::Gemm g{HB, Wt_dn, M, D, FF, nullptr, nullptr}; pg8::StaticOrder S; S.init(M, D, G, bid, 1);
;             EpiRes E{nullptr, nullptr, TB, p.in[z0 + 17] + (size_t)l * D, p.in[z0 + 18] + (size_t)l * D, ST2, Fold{ST1, nullptr, 0}}; pg8::gemm_phase<EpiRes>(lds, g, S, E, tid); } break;
.LBB0_96:
	s_andn2_b64 vcc, exec, s[0:1]
	s_cbranch_vccnz .LBB0_28
	s_mul_hi_i32 s0, s84, 0x66666667
	s_lshr_b32 s1, s0, 31
	s_ashr_i32 s0, s0, 2
	s_waitcnt lgkmcnt(0)
	s_add_i32 s4, s0, s1
	s_mul_i32 s0, s4, 10
	s_sub_i32 s85, s84, s0
	s_mov_b32 s2, s4
	s_add_u32 s0, s42, 0x1fd03600
	v_writelane_b32 v251, s2, 33
	s_addc_u32 s1, s43, 0
	s_nop 0
	v_writelane_b32 v251, s3, 34
	s_lshl_b32 s2, s4, 20
	s_and_b32 s2, s2, 0x100000
	s_lshl_b32 s4, s2, 2
	s_add_u32 s10, s0, s4
	s_addc_u32 s11, s1, 0
	s_xor_b32 s2, s2, 0x100000
	s_lshl_b32 s2, s2, 2
	s_add_u32 s0, s0, s2
	s_addc_u32 s1, s1, 0
	v_writelane_b32 v251, s0, 35
	s_nop 1
	v_writelane_b32 v251, s1, 36
	s_add_u32 s0, s42, 0x2e00000
	s_addc_u32 s1, s43, 0
	v_writelane_b32 v251, s0, 37
	s_nop 1
	v_writelane_b32 v251, s1, 38
	s_add_u32 s0, s42, 0x3400000
	s_addc_u32 s1, s43, 0
	v_writelane_b32 v251, s0, 39
	s_nop 1
	v_writelane_b32 v251, s1, 40
	s_add_u32 s0, s42, 0x5600000
	s_addc_u32 s1, s43, 0
	v_writelane_b32 v251, s0, 41
	s_nop 1
	v_writelane_b32 v251, s1, 42
	s_add_u32 s0, s42, 0xb600000
	s_addc_u32 s1, s43, 0
	v_writelane_b32 v251, s0, 43
	s_nop 1
	v_writelane_b32 v251, s1, 44
	s_add_u32 s0, s42, 0x1b600000
	s_addc_u32 s1, s43, 0
	v_writelane_b32 v251, s0, 45
	s_nop 1
	v_writelane_b32 v251, s1, 46
	s_add_u32 s0, s42, 0x1d600000
	s_addc_u32 s1, s43, 0
	v_writelane_b32 v251, s0, 47
	s_nop 1
	v_writelane_b32 v251, s1, 48
	s_add_u32 s0, s42, 0x1fa00000
	s_addc_u32 s1, s43, 0
	v_writelane_b32 v251, s0, 49
	s_cmp_lt_i32 s85, 5
	s_nop 0
	v_writelane_b32 v251, s1, 50
	v_writelane_b32 v251, s24, 51
	s_mov_b64 s[0:1], -1
	s_nop 0
	v_writelane_b32 v251, s25, 52
	v_writelane_b32 v251, s42, 53
	s_nop 1
	v_writelane_b32 v251, s43, 54
	s_cbranch_scc1 .LBB0_284
	s_add_u32 s8, s42, 0x3600000
	s_addc_u32 s9, s43, 0
	s_cmp_lt_i32 s85, 7
	s_cbranch_scc1 .LBB0_232
	s_cmp_lt_i32 s85, 8
	s_cbranch_scc1 .LBB0_183
	s_cmp_lt_i32 s85, 9
	s_cbranch_scc1 .LBB0_152
	s_cmp_eq_u32 s85, 9
	s_cbranch_scc0 .LBB0_151
	s_mov_b32 s100, 0x8000
	s_mov_b32 s101, 0
	v_readlane_b32 s0, v251, 29
	v_readlane_b32 s1, v251, 30
	s_mov_b32 s4, s0
	s_ashr_i32 s5, s0, 31
	v_writelane_b32 v251, s0, 29
	v_readfirstlane_b32 s12, v210
	s_nop 0
	v_writelane_b32 v251, s1, 30
	s_lshl_b64 s[0:1], s[4:5], 3
	v_readlane_b32 s4, v250, 40
	s_add_u32 s0, s68, s0
	v_readlane_b32 s5, v250, 41
	s_addc_u32 s1, s69, s1
	s_andn2_b64 vcc, exec, s[4:5]
	s_cbranch_vccnz .LBB0_110
	v_readlane_b32 s5, v251, 28
	s_ashr_i32 s2, s5, 31
	v_readlane_b32 s4, v250, 43
	s_add_u32 s6, s4, s5
	v_readlane_b32 s4, v250, 42
	s_addc_u32 s7, s4, s2
	v_cmp_gt_i64_e32 vcc, s[6:7], v[170:171]
	s_mov_b64 s[4:5], 0
	s_cbranch_vccnz .LBB0_109
	s_ashr_i32 s2, s6, 31
	s_lshr_b32 s2, s2, 29
	s_add_i32 s2, s6, s2
	s_and_b32 s4, s2, -8
	s_sub_i32 s6, s6, s4
	s_cmp_gt_i32 s6, -1
	s_mov_b64 s[4:5], -1
	s_cbranch_scc0 .LBB0_106
	s_lshl_b32 s7, s6, 6
	s_mov_b64 s[4:5], 0

; #define PG8_WAIT_V(n) asm volatile("s_waitcnt vmcnt(" #n ")" ::: "memory")
; #define PG8_BAR __builtin_amdgcn_s_barrier()
; template <class Epi>
; __device__ __forceinline__ void gemm_phase(LAS unsigned char* lds, const Gemm g, const StaticOrder& S, const Epi& E, const int tid) {
;     const int wid = __builtin_amdgcn_readfirstlane(tid >> 6), lane = tid & 63, wr = wid >> 2, wc = wid & 3, fr = lane & 15, fq = lane >> 4;
;     const int K = g.K, nt = K / BK, ntt = Epi::TWO ? 2 * nt : nt;
;     unsigned voffA[2], voffB[2];
; #pragma unroll
;     for (int i = 0; i < 2; ++i) { int R, C; stage_rc(tid * 16 + i * 8192, R, C); const int Rb = (R >> 5) * 64 + ((R >> 2) & 3) * 16 + ((R >> 4) & 1) * 4 + (R & 3);
;         voffA[i] = (unsigned)(R * K + C) * 2u; voffB[i] = (unsigned)(Rb * K + C) * 2u; }
;     const size_t kstep = (size_t)(BK * 2);
;     const size_t hstep = (size_t)HALF * K * 2;
;     const size_t tstep = 2 * hstep;
;     const size_t bhs = (size_t)8 * K * 2;
;     const unsigned ldsw = (unsigned)wid * 1024u;
;     const int aoff = lds_byte(wr * 64 + fr, fq * 8), boff = lds_byte(wc * 32 + fr, fq * 8);
;     ...
;     Unit cur, nxt; int ui = 0;
;     if (!S.next(0, cur)) return;
;     E.prepare(cur, lds, 0, tid);
;     f32x4 acc[2][2][4][2];
; #pragma unroll
;     for (int a = 0; a < 2; ++a)
; #pragma unroll
;         for (int b = 0; b < 2; ++b)
; #pragma unroll
;             for (int m = 0; m < 4; ++m)
; #pragma unroll
;                 for (int n = 0; n < 2; ++n) acc[a][b][m][n] = (f32x4){0.f, 0.f, 0.f, 0.f};
;     bf16x8 At[4][2], B0[2][2], B1[2][2];
;     const char* cA = (const char*)g.A + (size_t)cur.pm * tstep; const char* cB = (const char*)g.Bt + (size_t)cur.pn * tstep;
;     const char* cA2 = Epi::TWO ? (const char*)g.A2 + (size_t)cur.pm * tstep : cA; const char* cB2 = Epi::TWO ? (const char*)g.Bt2 + (size_t)cur.pn * tstep : cB;
;     if constexpr (SP2) {
;         PG8_STAGE(PG8_SB(0, 0), cB, voffB); PG8_STAGE(PG8_SB(0, 1), cB + bhs, voffB); PG8_STAGE(PG8_SA(0, 0), cA, voffA); PG8_STAGE(PG8_SA(0, 1), cA + hstep, voffA);
;         if (wr == 1) PG8_BAR;
;         PG8_WAIT_V(2); PG8_BAR;
;         PG8_STAGE(PG8_SB(1, 0), cB + kstep, voffB); PG8_STAGE(PG8_SA(1, 0), cA + kstep, voffA); PG8_STAGE(PG8_SB(1, 1), cB + bhs + kstep, voffB);
;         PG8_WAIT_V(6); PG8_BAR;
.LBB0_113:
	s_or_b64 exec, exec, s[4:5]
	v_ashrrev_i32_e32 v0, 31, v210
	v_lshrrev_b32_e32 v0, 26, v0
	v_add_u32_e32 v0, v210, v0
	v_ashrrev_i32_e32 v12, 6, v0
	v_bfe_i32 v0, v210, 27, 1
	v_lshlrev_b32_e32 v2, 4, v210
	v_lshrrev_b32_e32 v0, 22, v0
	v_add_u32_e32 v0, v2, v0
	v_and_b32_e32 v0, 0xfffffc00, v0
	v_sub_u32_e32 v0, v2, v0
	s_waitcnt lgkmcnt(1)
	v_lshrrev_b32_e32 v3, 4, v0
	v_bitop3_b32 v0, v3, v0, 32 bitop3:0x6c
	s_waitcnt lgkmcnt(0)
	v_ashrrev_i32_e32 v4, 31, v0
	v_lshrrev_b32_e32 v4, 26, v4
	v_add_u32_e32 v4, v0, v4
	v_lshlrev_b32_e32 v3, 3, v12
	v_ashrrev_i32_e32 v13, 6, v4
	v_and_b32_e32 v4, 0xc0, v4
	v_and_b32_e32 v3, -16, v3
	v_sub_u32_e32 v0, v0, v4
	v_add_u32_e32 v3, v13, v3
	v_ashrrev_i16_sdwa v0, v203, sext(v0) dst_sel:DWORD dst_unused:UNUSED_PAD src0_sel:DWORD src1_sel:BYTE_0
	v_lshlrev_b32_e32 v5, 5, v12
	v_bfe_i32 v14, v0, 0, 16
	v_lshlrev_b32_e32 v0, 1, v3
	v_lshlrev_b32_e32 v4, 2, v3
	v_lshrrev_b32_e32 v6, 2, v3
	v_and_b32_e32 v7, 3, v13
	v_and_b32_e32 v5, 32, v5
	v_and_b32_e32 v0, 0x3ffc0, v0
	v_and_b32_e32 v6, 4, v6
	v_and_or_b32 v4, v4, 48, v7
	v_or3_b32 v0, v4, v0, v6
	v_add_lshl_u32 v4, v5, v14, 1
	v_add_u32_e32 v2, 0x2000, v2
	v_lshl_add_u32 v162, v3, 7, v4
	v_ashrrev_i32_e32 v3, 31, v2
	v_lshrrev_b32_e32 v3, 22, v3
	v_add_u32_e32 v3, v2, v3
	v_ashrrev_i32_e32 v15, 10, v3
	v_mul_i32_i24_e32 v3, 0x400, v15
	v_sub_u32_e32 v2, v2, v3
	v_lshrrev_b32_e32 v3, 4, v2
	v_bitop3_b32 v2, v3, v2, 32 bitop3:0x6c
	v_lshl_add_u32 v0, v0, 14, v4
	v_ashrrev_i32_e32 v4, 31, v2
	v_lshrrev_b32_e32 v4, 26, v4
	v_add_u32_e32 v4, v2, v4
	s_ashr_i32 s2, s12, 6
	v_lshlrev_b32_e32 v3, 3, v15
	v_ashrrev_i32_e32 v16, 6, v4
	v_and_b32_e32 v4, 0xc0, v4
	s_ashr_i32 s27, s26, 31
	s_ashr_i32 s25, s24, 31
	v_and_b32_e32 v3, -16, v3
	v_sub_u32_e32 v2, v2, v4
	s_ashr_i32 s13, s12, 8
	s_lshl_b32 s36, s2, 10
	s_lshl_b64 s[4:5], s[26:27], 22
	s_lshl_b64 s[6:7], s[24:25], 22
	v_readlane_b32 s14, v251, 41
	v_add_u32_e32 v3, v16, v3
	v_ashrrev_i16_sdwa v2, v203, sext(v2) dst_sel:DWORD dst_unused:UNUSED_PAD src0_sel:DWORD src1_sel:BYTE_0
	v_readlane_b32 s15, v251, 42
	s_add_u32 s28, s14, s6
	v_lshlrev_b32_e32 v5, 5, v15
	v_bfe_i32 v17, v2, 0, 16
	v_lshlrev_b32_e32 v2, 1, v3
	v_lshlrev_b32_e32 v4, 2, v3
	v_lshrrev_b32_e32 v6, 2, v3
	v_and_b32_e32 v7, 3, v16
	s_addc_u32 s29, s15, s7
	s_add_i32 s37, s36, 0
	v_and_b32_e32 v5, 32, v5
	v_and_b32_e32 v2, 0x3ffc0, v2
	v_and_b32_e32 v6, 4, v6
	v_and_or_b32 v4, v4, 48, v7
	s_add_i32 m0, s37, 0x10000
	v_or3_b32 v2, v4, v2, v6
	v_add_lshl_u32 v4, v5, v17, 1
	global_load_lds_dwordx4 v0, s[28:29]
	s_add_i32 m0, s37, 0x12000
	v_lshl_add_u32 v166, v2, 14, v4
	s_add_u32 s6, s28, 0x20000
	global_load_lds_dwordx4 v166, s[28:29]
	s_addc_u32 s7, s29, 0
	s_add_i32 m0, s37, 0x14000
	v_lshl_add_u32 v164, v3, 7, v4
	global_load_lds_dwordx4 v0, s[6:7]
	s_add_i32 m0, s37, 0x16000
	v_mov_b32_e32 v167, v1
	global_load_lds_dwordx4 v166, s[6:7]
	v_readlane_b32 s6, v251, 43
	v_readlane_b32 s7, v251, 44
	s_add_u32 s30, s6, s4
	s_addc_u32 s31, s7, s5
	s_add_i32 s38, s37, 0x2000
	s_mov_b32 m0, s37
	s_add_u32 s4, s30, 0x4000
	global_load_lds_dwordx4 v162, s[30:31]
	s_mov_b32 m0, s38
	s_addc_u32 s5, s31, 0
	s_add_i32 s39, s37, 0x4000
	global_load_lds_dwordx4 v164, s[30:31]
	s_mov_b32 m0, s39
	s_add_i32 s44, s37, 0x6000
	global_load_lds_dwordx4 v162, s[4:5]
	s_mov_b32 m0, s44
	v_mov_b32_e32 v163, v1
	global_load_lds_dwordx4 v164, s[4:5]
	s_load_dwordx4 s[4:7], s[0:1], 0x88
	v_mov_b32_e32 v165, v1
	s_cmp_eq_u32 s13, 1
	v_lshl_add_u64 v[8:9], s[28:29], 0, v[0:1]
	v_lshl_add_u64 v[6:7], s[28:29], 0, v[166:167]
	v_lshl_add_u64 v[2:3], s[30:31], 0, v[162:163]
	s_cselect_b64 s[0:1], -1, 0
	s_cmp_lg_u32 s13, 1
	v_lshl_add_u64 v[4:5], s[30:31], 0, v[164:165]
	s_cbranch_scc1 .LBB0_115
	s_barrier
.LBB0_115:
	v_readlane_b32 s14, v251, 33
	v_readlane_b32 s15, v251, 34
	s_mov_b32 s16, s14
	s_ashr_i32 s17, s14, 31
	v_writelane_b32 v251, s14, 33
	v_bfe_u32 v19, v210, 4, 2
	v_and_b32_e32 v20, 15, v210
	v_writelane_b32 v251, s15, 34
	s_lshl_b64 s[14:15], s[16:17], 13
	s_waitcnt lgkmcnt(0)
	s_add_u32 s4, s4, s14
	s_addc_u32 s5, s5, s15
	s_add_u32 s6, s6, s14
	v_lshlrev_b32_e32 v21, 4, v19
	v_and_b32_e32 v18, 0xfc, v11
	s_addc_u32 s7, s7, s15
	s_and_b32 s2, s2, 3
	v_lshl_or_b32 v192, s13, 6, v20
	v_lshl_or_b32 v20, v20, 6, v21
	s_lshl_b32 s13, s13, 13
	v_and_b32_e32 v11, 32, v11
	s_add_i32 m0, s37, 0x18000
	v_lshl_add_u64 v[8:9], v[8:9], 0, s[70:71]
	v_bitop3_b32 v22, v20, s13, v11 bitop3:0xde
	s_lshl_b32 s13, s2, 12
	s_waitcnt vmcnt(2)
	s_barrier
	global_load_lds_dwordx4 v[8:9], off
	v_lshl_add_u64 v[6:7], v[6:7], 0, s[70:71]
	s_add_i32 m0, s37, 0x1a000
	s_add_i32 s45, s37, 0x8000
	s_add_i32 s46, s37, 0xa000
	global_load_lds_dwordx4 v[6:7], off
	v_lshl_add_u64 v[2:3], v[2:3], 0, s[100:101]
	s_mov_b32 m0, s45
	s_add_u32 s14, s28, 0x20080
	global_load_lds_dwordx4 v[2:3], off
	v_lshl_add_u64 v[2:3], v[4:5], 0, s[100:101]
	s_mov_b32 m0, s46
	s_addc_u32 s15, s29, 0
	global_load_lds_dwordx4 v[2:3], off
	s_add_i32 m0, s37, 0x1c000
	v_lshl_add_u64 v[2:3], s[14:15], 0, v[0:1]
	global_load_lds_dwordx4 v[2:3], off
	v_lshl_add_u64 v[2:3], s[14:15], 0, v[166:167]
	s_add_i32 m0, s37, 0x1e000
	v_lshlrev_b32_e32 v10, 5, v10
	global_load_lds_dwordx4 v[2:3], off
	v_readlane_b32 s16, v251, 35
	v_lshlrev_b32_e32 v2, 2, v10
	v_mov_b32_e32 v3, v1
	v_readlane_b32 s17, v251, 36
	s_waitcnt vmcnt(6)
	s_cmpk_lt_u32 s12, 0x100
	v_bitop3_b32 v193, s13, v20, v11 bitop3:0xf6
	v_lshl_add_u64 v[168:169], s[16:17], 0, v[2:3]
	v_lshlrev_b32_e32 v2, 10, v15
	v_and_b32_e32 v2, 0xfffff800, v2
	v_lshl_add_u32 v2, v16, 7, v2
	v_and_b32_e32 v3, 1, v15
	v_lshl_or_b32 v2, v3, 6, v2
	v_lshl_add_u32 v178, v17, 1, v2
	v_lshlrev_b32_e32 v2, 10, v12
	v_and_b32_e32 v2, 0xfffff800, v2
	v_lshl_add_u32 v2, v13, 7, v2
	v_and_b32_e32 v3, 1, v12
	s_cselect_b64 s[12:13], -1, 0
	s_add_i32 s14, 0, 0x20000
	v_readlane_b32 s15, v251, 28
	v_lshl_or_b32 v2, v3, 6, v2
	v_xor_b32_e32 v194, 64, v18
	v_xor_b32_e32 v195, 0x80, v18
	s_mov_b32 s25, 0
	v_cmp_eq_u32_e64 s[42:43], 0, v19
	v_lshl_add_u32 v196, v190, 3, s14
	s_ashr_i32 s47, s15, 31
	v_lshl_add_u32 v197, v192, 3, s14
	v_lshl_or_b32 v198, s2, 6, v21
	v_mov_b32_e32 v179, v1
	v_lshl_add_u32 v180, v14, 1, v2
	v_mov_b32_e32 v181, v1
	v_add_u32_e32 v199, 0, v22
	s_barrier
	s_branch .LBB0_118

; #define PG8_STAGE(bufoff, gbase, voff) do { _Pragma("unroll") for (int _i = 0; _i < 2; ++_i) \
;         __builtin_amdgcn_global_load_lds((const unsigned*)((const char*)(gbase) + (voff)[_i]), (LAS unsigned*)(lds + (bufoff) + ldsw + _i * 8192), 16, 0, 0); } while (0)
; #define PG8_LDA(dst, b, h) do { _Pragma("unroll") for (int m = 0; m < 4; ++m) _Pragma("unroll") for (int k = 0; k < 2; ++k) dst[m][k] = *(const LAS bf16x8*)(lds + PG8_SA(b, h) + aoff + m * 2048 + k * 1024); } while (0)
; #define PG8_LDB(dst, b, h) do { _Pragma("unroll") for (int n = 0; n < 2; ++n) _Pragma("unroll") for (int k = 0; k < 2; ++k) dst[n][k] = *(const LAS bf16x8*)(lds + PG8_SB(b, h) + boff + n * 2048 + k * 1024); } while (0)
; #define PG8_BAR __builtin_amdgcn_s_barrier()
; template <class Epi>
; __device__ __forceinline__ void gemm_phase(LAS unsigned char* lds, const Gemm g, const StaticOrder& S, const Epi& E, const int tid) {
;     ...
;         const bool has_next = S.next(ui + 1, nxt);
;         const char* nA = has_next ? (const char*)g.A + (size_t)nxt.pm * tstep : cA; const char* nB = has_next ? (const char*)g.Bt + (size_t)nxt.pn * tstep : cB;
;         for (int t = 0; t < ntt; t += 2) {
;             const bool last = (t == ntt - 2);
;             const bool s1 = Epi::TWO && (t >= nt), s2 = Epi::TWO && (t + 2 >= nt);
;             const char* a1 = (s1 ? cA2 + (size_t)(t - nt + 1) * kstep : cA + (size_t)(t + 1) * kstep);
;             const char* a2 = last ? nA : (s2 ? cA2 + (size_t)(t + 2 - nt) * kstep : cA + (size_t)(t + 2) * kstep);
;             const char* b2 = last ? nB : (s2 ? cB2 + (size_t)(t + 2 - nt) * kstep : cB + (size_t)(t + 2) * kstep);
;             const char* a3 = a2 + kstep; const char* b3 = b2 + kstep;
;             if constexpr (Epi::TWO) { if (t == nt) E.mid(acc, cur, wr, wc, fr, fq); }
;             if constexpr (SP2) {
;             PG8_LDB(B0, 0, 0); PG8_LDB(B1, 0, 1); PG8_SCHED; PG8_LDA(At, 0, 0); PG8_STAGE(PG8_SA(1, 1), a1 + hstep, voffA);
;             PG8_WAIT_V(8); PG8_WAIT_L(0); PG8_BAR; PG8_MMA(0, 0, At, B0); PG8_MMA(0, 1, At, B1); PG8_BAR; PG8_SCHED;
;     ...
; #pragma unroll
;         for (int a = 0; a < 2; ++a)
; #pragma unroll
;             for (int b = 0; b < 2; ++b)
; #pragma unroll
;                 for (int m = 0; m < 4; ++m)
; #pragma unroll
;                     for (int n = 0; n < 2; ++n) acc[a][b][m][n] = (f32x4){0.f, 0.f, 0.f, 0.f};
.LBB0_125:
	s_ashr_i32 s17, s16, 31
	s_lshl_b64 s[18:19], s[16:17], 22
	v_readlane_b32 s20, v251, 43
	v_readlane_b32 s21, v251, 44
	s_add_u32 s18, s20, s18
	s_addc_u32 s19, s21, s19
	s_and_b64 s[20:21], s[22:23], exec
	s_cselect_b32 s17, s19, s31
	s_cselect_b32 s27, s18, s30
	s_ashr_i32 s15, s14, 31
	s_lshl_b64 s[20:21], s[14:15], 22
	v_readlane_b32 s34, v251, 41
	v_readlane_b32 s35, v251, 42
	s_add_u32 s20, s34, s20
	s_addc_u32 s21, s35, s21
	s_and_b64 s[34:35], s[22:23], exec
	s_cselect_b32 s15, s21, s29
	s_cselect_b32 s33, s20, s28
	s_add_u32 s49, s28, 0x100
	s_addc_u32 s50, s29, 0
	s_add_u32 s28, s30, 0xc000
	v_mov_b32_e32 v2, 0
	s_addc_u32 s29, s31, 0
	s_mov_b32 s51, -2
	v_mov_b32_e32 v3, v2
	s_waitcnt lgkmcnt(0)
	v_mov_b32_e32 v4, v2
	v_mov_b32_e32 v5, v2
	v_mov_b32_e32 v6, v2
	v_mov_b32_e32 v7, v2
	v_mov_b32_e32 v8, v2
	v_mov_b32_e32 v9, v2
	v_mov_b32_e32 v34, v2
	v_mov_b32_e32 v35, v2
	v_mov_b32_e32 v36, v2
	v_mov_b32_e32 v37, v2
	v_mov_b32_e32 v38, v2
	v_mov_b32_e32 v39, v2
	v_mov_b32_e32 v40, v2
	v_mov_b32_e32 v41, v2
	v_mov_b32_e32 v66, v2
	v_mov_b32_e32 v67, v2
	v_mov_b32_e32 v68, v2
	v_mov_b32_e32 v69, v2
	v_mov_b32_e32 v70, v2
	v_mov_b32_e32 v71, v2
	v_mov_b32_e32 v72, v2
	v_mov_b32_e32 v73, v2
	v_mov_b32_e32 v82, v2
	v_mov_b32_e32 v83, v2
	v_mov_b32_e32 v84, v2
	v_mov_b32_e32 v85, v2
	v_mov_b32_e32 v86, v2
	v_mov_b32_e32 v87, v2
	v_mov_b32_e32 v88, v2
	v_mov_b32_e32 v89, v2
	v_mov_b32_e32 v10, v2
	v_mov_b32_e32 v11, v2
	v_mov_b32_e32 v12, v2
	v_mov_b32_e32 v13, v2
	v_mov_b32_e32 v14, v2
	v_mov_b32_e32 v15, v2
	v_mov_b32_e32 v16, v2
	v_mov_b32_e32 v17, v2
	v_mov_b32_e32 v58, v2
	v_mov_b32_e32 v59, v2
	v_mov_b32_e32 v60, v2
	v_mov_b32_e32 v61, v2
	v_mov_b32_e32 v62, v2
	v_mov_b32_e32 v63, v2
	v_mov_b32_e32 v64, v2
	v_mov_b32_e32 v65, v2
	v_mov_b32_e32 v74, v2
	v_mov_b32_e32 v75, v2
	v_mov_b32_e32 v76, v2
	v_mov_b32_e32 v77, v2
	v_mov_b32_e32 v78, v2
	v_mov_b32_e32 v79, v2
	v_mov_b32_e32 v80, v2
	v_mov_b32_e32 v81, v2
	v_mov_b32_e32 v90, v2
	v_mov_b32_e32 v91, v2
	v_mov_b32_e32 v92, v2
	v_mov_b32_e32 v93, v2
	v_mov_b32_e32 v94, v2
	v_mov_b32_e32 v95, v2
	v_mov_b32_e32 v96, v2
	v_mov_b32_e32 v97, v2
	v_mov_b32_e32 v98, v2
	v_mov_b32_e32 v99, v2
	v_mov_b32_e32 v100, v2
	v_mov_b32_e32 v101, v2
	v_mov_b32_e32 v102, v2
	v_mov_b32_e32 v103, v2
	v_mov_b32_e32 v104, v2
	v_mov_b32_e32 v105, v2
	v_mov_b32_e32 v114, v2
	v_mov_b32_e32 v115, v2
	v_mov_b32_e32 v116, v2
	v_mov_b32_e32 v117, v2
	v_mov_b32_e32 v118, v2
	v_mov_b32_e32 v119, v2
	v_mov_b32_e32 v120, v2
	v_mov_b32_e32 v121, v2
	v_mov_b32_e32 v130, v2
	v_mov_b32_e32 v131, v2
	v_mov_b32_e32 v132, v2
	v_mov_b32_e32 v133, v2
	v_mov_b32_e32 v134, v2
	v_mov_b32_e32 v135, v2
	v_mov_b32_e32 v136, v2
	v_mov_b32_e32 v137, v2
	v_mov_b32_e32 v146, v2
	v_mov_b32_e32 v147, v2
	v_mov_b32_e32 v148, v2
	v_mov_b32_e32 v149, v2
	v_mov_b32_e32 v150, v2
	v_mov_b32_e32 v151, v2
	v_mov_b32_e32 v152, v2
	v_mov_b32_e32 v153, v2
	v_mov_b32_e32 v106, v2
	v_mov_b32_e32 v107, v2
	v_mov_b32_e32 v108, v2
	v_mov_b32_e32 v109, v2
	v_mov_b32_e32 v110, v2
	v_mov_b32_e32 v111, v2
	v_mov_b32_e32 v112, v2
	v_mov_b32_e32 v113, v2
	v_mov_b32_e32 v122, v2
	v_mov_b32_e32 v123, v2
	v_mov_b32_e32 v124, v2
	v_mov_b32_e32 v125, v2
	v_mov_b32_e32 v126, v2
	v_mov_b32_e32 v127, v2
	v_mov_b32_e32 v128, v2
	v_mov_b32_e32 v129, v2
	v_mov_b32_e32 v138, v2
	v_mov_b32_e32 v139, v2
	v_mov_b32_e32 v140, v2
	v_mov_b32_e32 v141, v2
	v_mov_b32_e32 v142, v2
	v_mov_b32_e32 v143, v2
	v_mov_b32_e32 v144, v2
	v_mov_b32_e32 v145, v2
	v_mov_b32_e32 v154, v2
	v_mov_b32_e32 v155, v2
	v_mov_b32_e32 v156, v2
	v_mov_b32_e32 v157, v2
	v_mov_b32_e32 v158, v2
	v_mov_b32_e32 v159, v2
	v_mov_b32_e32 v160, v2
	v_mov_b32_e32 v161, v2
.LBB0_126:
	s_add_u32 s30, s28, 0x4000
	s_addc_u32 s31, s29, 0
	s_add_i32 s52, 0, 0x10000
	s_cmpk_eq_i32 s51, 0x7c
	s_cselect_b32 s35, s17, s31
	s_cselect_b32 s34, s27, s30
	s_cselect_b32 s31, s15, s50
	s_cselect_b32 s30, s33, s49
	s_add_i32 s54, 0, 0x14000
	v_add_u32_e32 v30, s52, v193
	v_add_u32_e32 v54, s54, v193
	ds_read_b128 v[18:21], v30
	ds_read_b128 v[22:25], v30 offset:1024
	ds_read_b128 v[26:29], v30 offset:2048
	ds_read_b128 v[30:33], v30 offset:3072
	ds_read_b128 v[42:45], v54
	ds_read_b128 v[46:49], v54 offset:1024
	ds_read_b128 v[50:53], v54 offset:2048
	ds_read_b128 v[54:57], v54 offset:3072
	v_lshl_add_u64 v[172:173], s[28:29], 0, v[180:181]
	s_add_i32 m0, s37, 0xc000
	ds_read_b128 v[182:185], v199
	global_load_lds_dwordx4 v[172:173], off
	ds_read_b128 v[186:189], v199 offset:1024
	ds_read_b128 v[212:215], v199 offset:2048
	v_lshl_add_u64 v[172:173], s[28:29], 0, v[178:179]
	s_add_i32 m0, s37, 0xe000
	s_nop 0
	global_load_lds_dwordx4 v[172:173], off
	ds_read_b128 v[216:219], v199 offset:3072
	ds_read_b128 v[220:223], v199 offset:4096
	ds_read_b128 v[224:227], v199 offset:5120
	ds_read_b128 v[228:231], v199 offset:6144
	ds_read_b128 v[232:235], v199 offset:7168
	s_waitcnt vmcnt(8)
	s_waitcnt lgkmcnt(0)
	s_barrier
; #define PG8_STAGE(bufoff, gbase, voff) do { _Pragma("unroll") for (int _i = 0; _i < 2; ++_i) \
;         __builtin_amdgcn_global_load_lds((const unsigned*)((const char*)(gbase) + (voff)[_i]), (LAS unsigned*)(lds + (bufoff) + ldsw + _i * 8192), 16, 0, 0); } while (0)
; #define PG8_LDA(dst, b, h) do { _Pragma("unroll") for (int m = 0; m < 4; ++m) _Pragma("unroll") for (int k = 0; k < 2; ++k) dst[m][k] = *(const LAS bf16x8*)(lds + PG8_SA(b, h) + aoff + m * 2048 + k * 1024); } while (0)
; #define PG8_MMA(ai, bj, At, Bt) do { __builtin_amdgcn_s_setprio(1); _Pragma("unroll") for (int m = 0; m < 4; ++m) _Pragma("unroll") for (int n = 0; n < 2; ++n) _Pragma("unroll") for (int k = 0; k < 2; ++k) \
;         acc[ai][bj][m][n] = __builtin_amdgcn_mfma_f32_16x16x32_bf16(Bt[n][k], At[m][k], acc[ai][bj][m][n], 0, 0, 0); __builtin_amdgcn_s_setprio(0); } while (0)
; #define PG8_WAIT_V(n) asm volatile("s_waitcnt vmcnt(" #n ")" ::: "memory")
; #define PG8_WAIT_L(n) asm volatile("s_waitcnt lgkmcnt(" #n ")" ::: "memory")
; #define PG8_BAR __builtin_amdgcn_s_barrier()
; #define PG8_SCHED __builtin_amdgcn_sched_barrier(0)
; template <class Epi>
; __device__ __forceinline__ void gemm_phase(LAS unsigned char* lds, const Gemm g, const StaticOrder& S, const Epi& E, const int tid) {
;     ...
;             PG8_WAIT_V(8); PG8_WAIT_L(0); PG8_BAR; PG8_MMA(0, 0, At, B0); PG8_MMA(0, 1, At, B1); PG8_BAR; PG8_SCHED;
;             PG8_LDA(At, 0, 1); PG8_STAGE(PG8_SB(0, 0), b2, voffB); PG8_STAGE(PG8_SB(0, 1), b2 + bhs, voffB); PG8_STAGE(PG8_SA(0, 0), a2, voffA);
;             PG8_WAIT_V(8); PG8_WAIT_L(0); PG8_BAR; PG8_MMA(1, 0, At, B0); PG8_MMA(1, 1, At, B1); PG8_BAR; PG8_SCHED;
	s_setprio 1
	s_waitcnt lgkmcnt(0)
	v_mfma_f32_16x16x32_bf16 v[158:161], v[18:21], v[182:185], v[158:161]
	v_mfma_f32_16x16x32_bf16 v[154:157], v[26:29], v[182:185], v[154:157]
	v_mfma_f32_16x16x32_bf16 v[142:145], v[18:21], v[212:215], v[142:145]
	v_mfma_f32_16x16x32_bf16 v[138:141], v[26:29], v[212:215], v[138:141]
	v_mfma_f32_16x16x32_bf16 v[126:129], v[18:21], v[220:223], v[126:129]
	v_mfma_f32_16x16x32_bf16 v[122:125], v[26:29], v[220:223], v[122:125]
	v_mfma_f32_16x16x32_bf16 v[110:113], v[18:21], v[228:231], v[110:113]
	v_mfma_f32_16x16x32_bf16 v[106:109], v[26:29], v[228:231], v[106:109]
	v_mfma_f32_16x16x32_bf16 v[158:161], v[22:25], v[186:189], v[158:161]
	v_mfma_f32_16x16x32_bf16 v[154:157], v[30:33], v[186:189], v[154:157]
	v_mfma_f32_16x16x32_bf16 v[142:145], v[22:25], v[216:219], v[142:145]
	v_mfma_f32_16x16x32_bf16 v[138:141], v[30:33], v[216:219], v[138:141]
	v_mfma_f32_16x16x32_bf16 v[126:129], v[22:25], v[224:227], v[126:129]
	v_mfma_f32_16x16x32_bf16 v[122:125], v[30:33], v[224:227], v[122:125]
	v_mfma_f32_16x16x32_bf16 v[110:113], v[22:25], v[232:235], v[110:113]
	v_mfma_f32_16x16x32_bf16 v[106:109], v[30:33], v[232:235], v[106:109]
	s_setprio 0
	s_setprio 1
	v_mfma_f32_16x16x32_bf16 v[150:153], v[42:45], v[182:185], v[150:153]
	v_mfma_f32_16x16x32_bf16 v[146:149], v[50:53], v[182:185], v[146:149]
	v_mfma_f32_16x16x32_bf16 v[134:137], v[42:45], v[212:215], v[134:137]
	v_mfma_f32_16x16x32_bf16 v[130:133], v[50:53], v[212:215], v[130:133]
	v_mfma_f32_16x16x32_bf16 v[118:121], v[42:45], v[220:223], v[118:121]
	v_mfma_f32_16x16x32_bf16 v[114:117], v[50:53], v[220:223], v[114:117]
	v_mfma_f32_16x16x32_bf16 v[102:105], v[42:45], v[228:231], v[102:105]
	v_mfma_f32_16x16x32_bf16 v[98:101], v[50:53], v[228:231], v[98:101]
	v_mfma_f32_16x16x32_bf16 v[150:153], v[46:49], v[186:189], v[150:153]
	v_mfma_f32_16x16x32_bf16 v[146:149], v[54:57], v[186:189], v[146:149]
	v_mfma_f32_16x16x32_bf16 v[134:137], v[46:49], v[216:219], v[134:137]
	v_mfma_f32_16x16x32_bf16 v[130:133], v[54:57], v[216:219], v[130:133]
	v_mfma_f32_16x16x32_bf16 v[118:121], v[46:49], v[224:227], v[118:121]
	v_mfma_f32_16x16x32_bf16 v[114:117], v[54:57], v[224:227], v[114:117]
	v_mfma_f32_16x16x32_bf16 v[102:105], v[46:49], v[232:235], v[102:105]
	v_mfma_f32_16x16x32_bf16 v[98:101], v[54:57], v[232:235], v[98:101]
	s_setprio 0
	s_barrier
	s_add_i32 s52, s52, s36
	v_lshl_add_u64 v[172:173], s[30:31], 0, v[0:1]
	s_mov_b32 m0, s52
	ds_read_b128 v[182:185], v199 offset:16384
	global_load_lds_dwordx4 v[172:173], off
	ds_read_b128 v[186:189], v199 offset:17408
	ds_read_b128 v[212:215], v199 offset:18432
	s_add_i32 m0, s52, 0x2000
	s_add_u32 s52, s30, 0x20000
	v_lshl_add_u64 v[174:175], s[30:31], 0, v[166:167]
	s_addc_u32 s53, s31, 0
	s_add_i32 s54, s54, s36
	global_load_lds_dwordx4 v[174:175], off
	ds_read_b128 v[216:219], v199 offset:19456
	ds_read_b128 v[220:223], v199 offset:20480
	v_lshl_add_u64 v[176:177], s[52:53], 0, v[0:1]
	s_mov_b32 m0, s54
	v_lshl_add_u64 v[200:201], s[34:35], 0, v[164:165]
	global_load_lds_dwordx4 v[176:177], off
	ds_read_b128 v[224:227], v199 offset:21504
	ds_read_b128 v[228:231], v199 offset:22528
	v_lshl_add_u64 v[176:177], s[52:53], 0, v[166:167]
	s_add_i32 m0, s54, 0x2000
	s_nop 0
	global_load_lds_dwordx4 v[176:177], off
	ds_read_b128 v[232:235], v199 offset:23552
	v_lshl_add_u64 v[176:177], s[34:35], 0, v[162:163]
	s_mov_b32 m0, s37
	s_nop 0
	global_load_lds_dwordx4 v[176:177], off
	s_mov_b32 m0, s38
	s_nop 0
	global_load_lds_dwordx4 v[200:201], off
	s_waitcnt vmcnt(8)
	s_waitcnt lgkmcnt(0)
	s_barrier
	s_setprio 1
	s_waitcnt lgkmcnt(0)
	v_mfma_f32_16x16x32_bf16 v[94:97], v[18:21], v[182:185], v[94:97]
	v_mfma_f32_16x16x32_bf16 v[90:93], v[26:29], v[182:185], v[90:93]
	v_mfma_f32_16x16x32_bf16 v[78:81], v[18:21], v[212:215], v[78:81]
	v_mfma_f32_16x16x32_bf16 v[74:77], v[26:29], v[212:215], v[74:77]
	v_mfma_f32_16x16x32_bf16 v[62:65], v[18:21], v[220:223], v[62:65]
	v_mfma_f32_16x16x32_bf16 v[58:61], v[26:29], v[220:223], v[58:61]
	v_mfma_f32_16x16x32_bf16 v[14:17], v[18:21], v[228:231], v[14:17]
	v_mfma_f32_16x16x32_bf16 v[10:13], v[26:29], v[228:231], v[10:13]
	v_mfma_f32_16x16x32_bf16 v[94:97], v[22:25], v[186:189], v[94:97]
	v_mfma_f32_16x16x32_bf16 v[90:93], v[30:33], v[186:189], v[90:93]
	v_mfma_f32_16x16x32_bf16 v[78:81], v[22:25], v[216:219], v[78:81]
	v_mfma_f32_16x16x32_bf16 v[74:77], v[30:33], v[216:219], v[74:77]
	v_mfma_f32_16x16x32_bf16 v[62:65], v[22:25], v[224:227], v[62:65]
	v_mfma_f32_16x16x32_bf16 v[58:61], v[30:33], v[224:227], v[58:61]
	v_mfma_f32_16x16x32_bf16 v[14:17], v[22:25], v[232:235], v[14:17]
	v_mfma_f32_16x16x32_bf16 v[10:13], v[30:33], v[232:235], v[10:13]
	s_setprio 0
	s_setprio 1
	v_mfma_f32_16x16x32_bf16 v[38:41], v[42:45], v[220:223], v[38:41]
	v_mfma_f32_16x16x32_bf16 v[34:37], v[50:53], v[220:223], v[34:37]
	v_mfma_f32_16x16x32_bf16 v[6:9], v[42:45], v[228:231], v[6:9]
	v_mfma_f32_16x16x32_bf16 v[2:5], v[50:53], v[228:231], v[2:5]
	v_mfma_f32_16x16x32_bf16 v[18:21], v[42:45], v[182:185], v[86:89]
	v_mfma_f32_16x16x32_bf16 v[22:25], v[50:53], v[182:185], v[82:85]
	v_mfma_f32_16x16x32_bf16 v[26:29], v[42:45], v[212:215], v[70:73]
	v_mfma_f32_16x16x32_bf16 v[30:33], v[50:53], v[212:215], v[66:69]
	v_mfma_f32_16x16x32_bf16 v[38:41], v[46:49], v[224:227], v[38:41]
	v_mfma_f32_16x16x32_bf16 v[34:37], v[54:57], v[224:227], v[34:37]
	v_mfma_f32_16x16x32_bf16 v[6:9], v[46:49], v[232:235], v[6:9]
	v_mfma_f32_16x16x32_bf16 v[2:5], v[54:57], v[232:235], v[2:5]
	v_mfma_f32_16x16x32_bf16 v[18:21], v[46:49], v[186:189], v[18:21]
	v_mfma_f32_16x16x32_bf16 v[22:25], v[54:57], v[186:189], v[22:25]
	v_mfma_f32_16x16x32_bf16 v[26:29], v[46:49], v[216:219], v[26:29]
	v_mfma_f32_16x16x32_bf16 v[30:33], v[54:57], v[216:219], v[30:33]
	s_setprio 0
	s_barrier
; #define PG8_STAGE(bufoff, gbase, voff) do { _Pragma("unroll") for (int _i = 0; _i < 2; ++_i) \
;         __builtin_amdgcn_global_load_lds((const unsigned*)((const char*)(gbase) + (voff)[_i]), (LAS unsigned*)(lds + (bufoff) + ldsw + _i * 8192), 16, 0, 0); } while (0)
; #define PG8_LDA(dst, b, h) do { _Pragma("unroll") for (int m = 0; m < 4; ++m) _Pragma("unroll") for (int k = 0; k < 2; ++k) dst[m][k] = *(const LAS bf16x8*)(lds + PG8_SA(b, h) + aoff + m * 2048 + k * 1024); } while (0)
; #define PG8_LDB(dst, b, h) do { _Pragma("unroll") for (int n = 0; n < 2; ++n) _Pragma("unroll") for (int k = 0; k < 2; ++k) dst[n][k] = *(const LAS bf16x8*)(lds + PG8_SB(b, h) + boff + n * 2048 + k * 1024); } while (0)
; #define PG8_MMA(ai, bj, At, Bt) do { __builtin_amdgcn_s_setprio(1); _Pragma("unroll") for (int m = 0; m < 4; ++m) _Pragma("unroll") for (int n = 0; n < 2; ++n) _Pragma("unroll") for (int k = 0; k < 2; ++k) \
;         acc[ai][bj][m][n] = __builtin_amdgcn_mfma_f32_16x16x32_bf16(Bt[n][k], At[m][k], acc[ai][bj][m][n], 0, 0, 0); __builtin_amdgcn_s_setprio(0); } while (0)
; #define PG8_WAIT_V(n) asm volatile("s_waitcnt vmcnt(" #n ")" ::: "memory")
; #define PG8_WAIT_L(n) asm volatile("s_waitcnt lgkmcnt(" #n ")" ::: "memory")
; #define PG8_BAR __builtin_amdgcn_s_barrier()
; #define PG8_SCHED __builtin_amdgcn_sched_barrier(0)
; template <class Epi>
; __device__ __forceinline__ void gemm_phase(LAS unsigned char* lds, const Gemm g, const StaticOrder& S, const Epi& E, const int tid) {
;     ...
;             PG8_LDB(B0, 1, 0); PG8_LDB(B1, 1, 1); PG8_SCHED; PG8_LDA(At, 1, 0); PG8_STAGE(PG8_SA(0, 1), a2 + hstep, voffA);
;             PG8_WAIT_V(8); PG8_WAIT_L(0); PG8_BAR; PG8_MMA(0, 0, At, B0); PG8_MMA(0, 1, At, B1); PG8_BAR; PG8_SCHED;
	s_add_i32 s52, 0, 0x18000
	s_add_i32 s53, 0, 0x1c000
	v_add_u32_e32 v54, s52, v193
	v_add_u32_e32 v66, s53, v193
	ds_read_b128 v[42:45], v54
	ds_read_b128 v[46:49], v54 offset:1024
	ds_read_b128 v[50:53], v54 offset:2048
	ds_read_b128 v[54:57], v54 offset:3072
	ds_read_b128 v[182:185], v66
	ds_read_b128 v[186:189], v66 offset:1024
	ds_read_b128 v[212:215], v66 offset:2048
	ds_read_b128 v[216:219], v66 offset:3072
	s_add_u32 s34, s34, 0x4000
	s_addc_u32 s35, s35, 0
	s_mov_b32 m0, s39
	v_lshl_add_u64 v[236:237], s[34:35], 0, v[162:163]
	ds_read_b128 v[66:69], v199 offset:32768
	global_load_lds_dwordx4 v[236:237], off
	ds_read_b128 v[70:73], v199 offset:33792
	ds_read_b128 v[82:85], v199 offset:34816
	v_lshl_add_u64 v[236:237], s[34:35], 0, v[164:165]
	s_mov_b32 m0, s44
	s_nop 0
	global_load_lds_dwordx4 v[236:237], off
	ds_read_b128 v[86:89], v199 offset:35840
	ds_read_b128 v[220:223], v199 offset:36864
	ds_read_b128 v[224:227], v199 offset:37888
	ds_read_b128 v[228:231], v199 offset:38912
	ds_read_b128 v[232:235], v199 offset:39936
	s_waitcnt vmcnt(8)
	s_waitcnt lgkmcnt(0)
	s_barrier
	s_setprio 1
	s_waitcnt lgkmcnt(0)
	v_mfma_f32_16x16x32_bf16 v[158:161], v[42:45], v[66:69], v[158:161]
	v_mfma_f32_16x16x32_bf16 v[154:157], v[50:53], v[66:69], v[154:157]
	v_mfma_f32_16x16x32_bf16 v[142:145], v[42:45], v[82:85], v[142:145]
	v_mfma_f32_16x16x32_bf16 v[138:141], v[50:53], v[82:85], v[138:141]
	v_mfma_f32_16x16x32_bf16 v[126:129], v[42:45], v[220:223], v[126:129]
	v_mfma_f32_16x16x32_bf16 v[122:125], v[50:53], v[220:223], v[122:125]
	v_mfma_f32_16x16x32_bf16 v[110:113], v[42:45], v[228:231], v[110:113]
	v_mfma_f32_16x16x32_bf16 v[106:109], v[50:53], v[228:231], v[106:109]
	v_mfma_f32_16x16x32_bf16 v[158:161], v[46:49], v[70:73], v[158:161]
	v_mfma_f32_16x16x32_bf16 v[154:157], v[54:57], v[70:73], v[154:157]
	v_mfma_f32_16x16x32_bf16 v[142:145], v[46:49], v[86:89], v[142:145]
	v_mfma_f32_16x16x32_bf16 v[138:141], v[54:57], v[86:89], v[138:141]
	v_mfma_f32_16x16x32_bf16 v[126:129], v[46:49], v[224:227], v[126:129]
	v_mfma_f32_16x16x32_bf16 v[122:125], v[54:57], v[224:227], v[122:125]
	v_mfma_f32_16x16x32_bf16 v[110:113], v[46:49], v[232:235], v[110:113]
	v_mfma_f32_16x16x32_bf16 v[106:109], v[54:57], v[232:235], v[106:109]
	s_setprio 0
	s_setprio 1
	v_mfma_f32_16x16x32_bf16 v[150:153], v[182:185], v[66:69], v[150:153]
	v_mfma_f32_16x16x32_bf16 v[66:69], v[212:215], v[66:69], v[146:149]
	v_mfma_f32_16x16x32_bf16 v[146:149], v[216:219], v[70:73], v[66:69]
	v_mfma_f32_16x16x32_bf16 v[66:69], v[182:185], v[82:85], v[134:137]
	v_mfma_f32_16x16x32_bf16 v[134:137], v[186:189], v[86:89], v[66:69]
	v_mfma_f32_16x16x32_bf16 v[66:69], v[212:215], v[82:85], v[130:133]
	v_mfma_f32_16x16x32_bf16 v[130:133], v[216:219], v[86:89], v[66:69]
	v_mfma_f32_16x16x32_bf16 v[66:69], v[182:185], v[220:223], v[118:121]
	v_mfma_f32_16x16x32_bf16 v[118:121], v[186:189], v[224:227], v[66:69]
	v_mfma_f32_16x16x32_bf16 v[66:69], v[212:215], v[220:223], v[114:117]
	v_mfma_f32_16x16x32_bf16 v[114:117], v[216:219], v[224:227], v[66:69]
	v_mfma_f32_16x16x32_bf16 v[66:69], v[182:185], v[228:231], v[102:105]
	v_mfma_f32_16x16x32_bf16 v[102:105], v[186:189], v[232:235], v[66:69]
	v_mfma_f32_16x16x32_bf16 v[66:69], v[212:215], v[228:231], v[98:101]
	v_mfma_f32_16x16x32_bf16 v[150:153], v[186:189], v[70:73], v[150:153]
	v_mfma_f32_16x16x32_bf16 v[98:101], v[216:219], v[232:235], v[66:69]
	s_setprio 0
	s_barrier
; #define PG8_STAGE(bufoff, gbase, voff) do { _Pragma("unroll") for (int _i = 0; _i < 2; ++_i) \
;         __builtin_amdgcn_global_load_lds((const unsigned*)((const char*)(gbase) + (voff)[_i]), (LAS unsigned*)(lds + (bufoff) + ldsw + _i * 8192), 16, 0, 0); } while (0)
; #define PG8_LDA(dst, b, h) do { _Pragma("unroll") for (int m = 0; m < 4; ++m) _Pragma("unroll") for (int k = 0; k < 2; ++k) dst[m][k] = *(const LAS bf16x8*)(lds + PG8_SA(b, h) + aoff + m * 2048 + k * 1024); } while (0)
; #define PG8_MMA(ai, bj, At, Bt) do { __builtin_amdgcn_s_setprio(1); _Pragma("unroll") for (int m = 0; m < 4; ++m) _Pragma("unroll") for (int n = 0; n < 2; ++n) _Pragma("unroll") for (int k = 0; k < 2; ++k) \
;         acc[ai][bj][m][n] = __builtin_amdgcn_mfma_f32_16x16x32_bf16(Bt[n][k], At[m][k], acc[ai][bj][m][n], 0, 0, 0); __builtin_amdgcn_s_setprio(0); } while (0)
; #define PG8_WAIT_V(n) asm volatile("s_waitcnt vmcnt(" #n ")" ::: "memory")
; #define PG8_WAIT_L(n) asm volatile("s_waitcnt lgkmcnt(" #n ")" ::: "memory")
; #define PG8_BAR __builtin_amdgcn_s_barrier()
; #define PG8_SCHED __builtin_amdgcn_sched_barrier(0)
; template <class Epi>
; __device__ __forceinline__ void gemm_phase(LAS unsigned char* lds, const Gemm g, const StaticOrder& S, const Epi& E, const int tid) {
;     ...
;             const char* a1 = (s1 ? cA2 + (size_t)(t - nt + 1) * kstep : cA + (size_t)(t + 1) * kstep);
;             const char* a2 = last ? nA : (s2 ? cA2 + (size_t)(t + 2 - nt) * kstep : cA + (size_t)(t + 2) * kstep);
;             const char* b2 = last ? nB : (s2 ? cB2 + (size_t)(t + 2 - nt) * kstep : cB + (size_t)(t + 2) * kstep);
;             const char* a3 = a2 + kstep; const char* b3 = b2 + kstep;
;     ...
;             PG8_LDA(At, 1, 1); PG8_STAGE(PG8_SB(1, 0), b3, voffB); PG8_STAGE(PG8_SB(1, 1), b3 + bhs, voffB); PG8_STAGE(PG8_SA(1, 0), a3, voffA);
;             PG8_WAIT_V(8); PG8_WAIT_L(0); PG8_BAR; PG8_MMA(1, 0, At, B0); PG8_MMA(1, 1, At, B1); PG8_BAR; PG8_SCHED;
	s_add_i32 s34, s52, s36
	v_lshl_add_u64 v[82:83], v[172:173], 0, s[70:71]
	s_mov_b32 m0, s34
	s_nop 0
	ds_read_b128 v[66:69], v199 offset:49152
	global_load_lds_dwordx4 v[82:83], off
	ds_read_b128 v[70:73], v199 offset:50176
	ds_read_b128 v[220:223], v199 offset:51200
	s_add_i32 m0, s34, 0x2000
	s_add_u32 s30, s30, 0x20080
	v_lshl_add_u64 v[82:83], v[174:175], 0, s[70:71]
	s_addc_u32 s31, s31, 0
	s_add_i32 s34, s53, s36
	global_load_lds_dwordx4 v[82:83], off
	ds_read_b128 v[224:227], v199 offset:52224
	ds_read_b128 v[228:231], v199 offset:53248
	v_lshl_add_u64 v[82:83], s[30:31], 0, v[0:1]
	s_mov_b32 m0, s34
	s_nop 0
	global_load_lds_dwordx4 v[82:83], off
	ds_read_b128 v[232:235], v199 offset:54272
	ds_read_b128 v[236:239], v199 offset:55296
	v_lshl_add_u64 v[82:83], s[30:31], 0, v[166:167]
	s_add_i32 m0, s34, 0x2000
	s_nop 0
	global_load_lds_dwordx4 v[82:83], off
	ds_read_b128 v[240:243], v199 offset:56320
	v_lshl_add_u64 v[82:83], v[176:177], 0, s[100:101]
	s_mov_b32 m0, s45
	s_nop 0
	global_load_lds_dwordx4 v[82:83], off
	v_lshl_add_u64 v[82:83], v[200:201], 0, s[100:101]
	s_mov_b32 m0, s46
	s_nop 0
	global_load_lds_dwordx4 v[82:83], off
	s_waitcnt vmcnt(8)
	s_waitcnt lgkmcnt(0)
	s_barrier
	s_setprio 1
	s_waitcnt lgkmcnt(0)
	v_mfma_f32_16x16x32_bf16 v[82:85], v[42:45], v[66:69], v[94:97]
	v_mfma_f32_16x16x32_bf16 v[94:97], v[46:49], v[70:73], v[82:85]
	v_mfma_f32_16x16x32_bf16 v[82:85], v[50:53], v[66:69], v[90:93]
	v_mfma_f32_16x16x32_bf16 v[78:81], v[42:45], v[220:223], v[78:81]
	v_mfma_f32_16x16x32_bf16 v[74:77], v[50:53], v[220:223], v[74:77]
	v_mfma_f32_16x16x32_bf16 v[62:65], v[42:45], v[228:231], v[62:65]
	v_mfma_f32_16x16x32_bf16 v[58:61], v[50:53], v[228:231], v[58:61]
	v_mfma_f32_16x16x32_bf16 v[14:17], v[42:45], v[236:239], v[14:17]
	v_mfma_f32_16x16x32_bf16 v[10:13], v[50:53], v[236:239], v[10:13]
	v_mfma_f32_16x16x32_bf16 v[90:93], v[54:57], v[70:73], v[82:85]
	v_mfma_f32_16x16x32_bf16 v[78:81], v[46:49], v[224:227], v[78:81]
	v_mfma_f32_16x16x32_bf16 v[74:77], v[54:57], v[224:227], v[74:77]
	v_mfma_f32_16x16x32_bf16 v[62:65], v[46:49], v[232:235], v[62:65]
	v_mfma_f32_16x16x32_bf16 v[58:61], v[54:57], v[232:235], v[58:61]
	v_mfma_f32_16x16x32_bf16 v[14:17], v[46:49], v[240:243], v[14:17]
	v_mfma_f32_16x16x32_bf16 v[10:13], v[54:57], v[240:243], v[10:13]
	s_setprio 0
	s_setprio 1
	v_mfma_f32_16x16x32_bf16 v[18:21], v[182:185], v[66:69], v[18:21]
	v_mfma_f32_16x16x32_bf16 v[86:89], v[186:189], v[70:73], v[18:21]
	v_mfma_f32_16x16x32_bf16 v[18:21], v[212:215], v[66:69], v[22:25]
	v_mfma_f32_16x16x32_bf16 v[82:85], v[216:219], v[70:73], v[18:21]
	v_mfma_f32_16x16x32_bf16 v[18:21], v[182:185], v[220:223], v[26:29]
	v_mfma_f32_16x16x32_bf16 v[70:73], v[186:189], v[224:227], v[18:21]
	v_mfma_f32_16x16x32_bf16 v[18:21], v[212:215], v[220:223], v[30:33]
	v_mfma_f32_16x16x32_bf16 v[66:69], v[216:219], v[224:227], v[18:21]
	v_mfma_f32_16x16x32_bf16 v[18:21], v[182:185], v[228:231], v[38:41]
	v_mfma_f32_16x16x32_bf16 v[38:41], v[186:189], v[232:235], v[18:21]
	v_mfma_f32_16x16x32_bf16 v[18:21], v[212:215], v[228:231], v[34:37]
	v_mfma_f32_16x16x32_bf16 v[6:9], v[182:185], v[236:239], v[6:9]
	v_mfma_f32_16x16x32_bf16 v[2:5], v[212:215], v[236:239], v[2:5]
	v_mfma_f32_16x16x32_bf16 v[34:37], v[216:219], v[232:235], v[18:21]
	v_mfma_f32_16x16x32_bf16 v[6:9], v[186:189], v[240:243], v[6:9]
	v_mfma_f32_16x16x32_bf16 v[2:5], v[216:219], v[240:243], v[2:5]
	s_setprio 0
	s_barrier
	s_add_i32 s51, s51, 2
	s_add_u32 s49, s49, 0x100
	s_addc_u32 s50, s50, 0
	s_add_u32 s28, s28, 0x10000
	s_addc_u32 s29, s29, 0
	s_cmpk_gt_u32 s51, 0x7d
	s_cbranch_scc0 .LBB0_126
	s_and_b64 vcc, exec, s[12:13]
	s_cbranch_vccz .LBB0_129
	s_barrier

; __device__ __forceinline__ float bf_lo(unsigned w) { return __uint_as_float(w << 16); }
; __device__ __forceinline__ float bf_hi(unsigned w) { return __uint_as_float(w & 0xffff0000u); }
; __device__ __forceinline__ u32x4 pack8(const f32x4 a, const f32x4 b) { u32x4 w; w.x = cvt_pk_bf16(a[0], a[1]); w.y = cvt_pk_bf16(a[2], a[3]); w.z = cvt_pk_bf16(b[0], b[1]); w.w = cvt_pk_bf16(b[2], b[3]); return w; }
;     __device__ __forceinline__ void operator()(const f32x4 (&acc)[2][2][4][2], const pg8::Unit& u, int wr, int wc, int fr, int fq, LAS unsigned char* lds, int par) const {
;     ...
;         const int row0 = u.pm * 256 + wr * 64 + fr, c0 = u.pn * 256 + wc * 64 + 16 * fq;
; #pragma unroll
;         for (int ai = 0; ai < 2; ++ai)
; #pragma unroll
;             for (int m = 0; m < 4; ++m) {
;                 const int row = row0 + ai * 128 + m * 16, lrow = ai * 128 + wr * 64 + m * 16 + fr;
;                 float mu = 0.f, rstd = 1.f; if (fold) { mu = rsb[2 * lrow]; rstd = rsb[2 * lrow + 1]; }
; #pragma unroll
;                 for (int bj = 0; bj < 2; ++bj) {
;                     const size_t off = (size_t)row * ld + c0 + bj * 8;
;                     f32x4 v0 = acc[ai][bj][m][0], v1 = acc[ai][bj][m][1];
;                     if (fold) fold_apply(v0, v1, mu, rstd, cvb, wc * 64 + 16 * fq + bj * 8);
;                     if (MODE == 0) { v0 *= scale; v1 *= scale; }
;                     if (MODE == 1) {
; #pragma unroll
;                         for (int j = 0; j < 4; ++j) { const float a = fmaxf(v0[j], 0.f), b = fmaxf(v1[j], 0.f); v0[j] = a * a; v1[j] = b * b; }
;                     }
;                     if (MODE == 2 || MODE == 3) {
;                         const u32x4 gw = *(const u32x4*)(gate + off);
;                         v0[0] *= bf_lo(gw.x); v0[1] *= bf_hi(gw.x); v0[2] *= bf_lo(gw.y); v0[3] *= bf_hi(gw.y);
;                         v1[0] *= bf_lo(gw.z); v1[1] *= bf_hi(gw.z); v1[2] *= bf_lo(gw.w); v1[3] *= bf_hi(gw.w);
;                     }
;                     if (MODE == 3) {
;                         const u32x4 pw = *(const u32x4*)(o + off);
;                         v0[0] += bf_lo(pw.x); v0[1] += bf_hi(pw.x); v0[2] += bf_lo(pw.y); v0[3] += bf_hi(pw.y);
;                         v1[0] += bf_lo(pw.z); v1[1] += bf_hi(pw.z); v1[2] += bf_lo(pw.w); v1[3] += bf_hi(pw.w);
;                     }
;                     *(u32x4*)(o + off) = pack8(v0, v1);
.LBB0_176:
	s_and_b32 s15, s41, 1
	v_lshl_add_u32 v156, s15, 12, v153
	v_lshl_add_u32 v157, s15, 11, v152
	v_readlane_b32 s26, v251, 43
	v_readlane_b32 s27, v251, 44
	ds_read_b128 v[212:215], v156
	ds_read_b128 v[216:219], v156 offset:16
	ds_read_b128 v[220:223], v156 offset:32
	ds_read_b128 v[224:227], v156 offset:48
	ds_read_b128 v[228:231], v156 offset:64
	ds_read_b128 v[232:235], v156 offset:80
	ds_read_b128 v[236:239], v156 offset:96
	ds_read_b128 v[240:243], v156 offset:112
	ds_read_b64 v[172:173], v157
	ds_read_b64 v[174:175], v157 offset:128
	ds_read_b64 v[176:177], v157 offset:256
	ds_read_b64 v[178:179], v157 offset:384
	ds_read_b64 v[180:181], v157 offset:1024
	ds_read_b64 v[182:183], v157 offset:1152
	ds_read_b64 v[184:185], v157 offset:1280
	ds_read_b64 v[186:187], v157 offset:1408
	v_lshl_add_u32 v158, s24, 15, v148
	v_lshl_or_b32 v159, s40, 8, v150
	v_lshlrev_b32_e32 v201, 7, v158
	v_lshrrev_b32_e32 v158, 6, v159
	v_and_b32_e32 v159, 63, v159
	v_lshl_add_u32 v201, v158, 15, v201
	v_lshl_add_u32 v201, v159, 1, v201
	s_waitcnt lgkmcnt(0)
	v_mul_f32_e32 v200, v173, v172
	v_mov_b32_e32 v155, v201
	v_fma_f32 v188, -v200, v212, v213
	v_fma_f32 v189, -v200, v214, v215
	v_fma_f32 v190, -v200, v216, v217
	v_fma_f32 v191, -v200, v218, v219
	v_fma_f32 v192, -v200, v220, v221
	v_fma_f32 v193, -v200, v222, v223
	v_fma_f32 v194, -v200, v224, v225
	v_fma_f32 v195, -v200, v226, v227
	v_fma_f32 v126, v173, v126, v188
	v_fma_f32 v127, v173, v127, v189
	v_fma_f32 v128, v173, v128, v190
	v_fma_f32 v129, v173, v129, v191
	v_fma_f32 v122, v173, v122, v192
	v_fma_f32 v123, v173, v123, v193
	v_fma_f32 v124, v173, v124, v194
	v_fma_f32 v125, v173, v125, v195
	v_max_f32_e32 v126, 0, v126
	v_max_f32_e32 v127, 0, v127
	v_max_f32_e32 v128, 0, v128
	v_max_f32_e32 v129, 0, v129
	v_max_f32_e32 v122, 0, v122
	v_max_f32_e32 v123, 0, v123
	v_max_f32_e32 v124, 0, v124
	v_max_f32_e32 v125, 0, v125
	v_mul_f32_e32 v126, v126, v126
	v_mul_f32_e32 v127, v127, v127
	v_mul_f32_e32 v128, v128, v128
	v_mul_f32_e32 v129, v129, v129
	v_mul_f32_e32 v122, v122, v122
	v_mul_f32_e32 v123, v123, v123
	v_mul_f32_e32 v124, v124, v124
	v_mul_f32_e32 v125, v125, v125
	v_cvt_pk_bf16_f32 v196, v126, v127
	v_cvt_pk_bf16_f32 v197, v128, v129
	v_cvt_pk_bf16_f32 v198, v122, v123
	v_cvt_pk_bf16_f32 v199, v124, v125
	global_store_dwordx4 v155, v[196:199], s[26:27]
	v_fma_f32 v188, -v200, v228, v229
	v_fma_f32 v189, -v200, v230, v231
	v_fma_f32 v190, -v200, v232, v233
	v_fma_f32 v191, -v200, v234, v235
	v_fma_f32 v192, -v200, v236, v237
	v_fma_f32 v193, -v200, v238, v239
	v_fma_f32 v194, -v200, v240, v241
	v_fma_f32 v195, -v200, v242, v243
	v_fma_f32 v118, v173, v118, v188
	v_fma_f32 v119, v173, v119, v189
	v_fma_f32 v120, v173, v120, v190
	v_fma_f32 v121, v173, v121, v191
	v_fma_f32 v114, v173, v114, v192
	v_fma_f32 v115, v173, v115, v193
	v_fma_f32 v116, v173, v116, v194
	v_fma_f32 v117, v173, v117, v195
	v_max_f32_e32 v118, 0, v118
	v_max_f32_e32 v119, 0, v119
	v_max_f32_e32 v120, 0, v120
	v_max_f32_e32 v121, 0, v121
	v_max_f32_e32 v114, 0, v114
	v_max_f32_e32 v115, 0, v115
	v_max_f32_e32 v116, 0, v116
	v_max_f32_e32 v117, 0, v117
	v_mul_f32_e32 v118, v118, v118
	v_mul_f32_e32 v119, v119, v119
	v_mul_f32_e32 v120, v120, v120
	v_mul_f32_e32 v121, v121, v121
	v_mul_f32_e32 v114, v114, v114
	v_mul_f32_e32 v115, v115, v115
	v_mul_f32_e32 v116, v116, v116
	v_mul_f32_e32 v117, v117, v117
	v_cvt_pk_bf16_f32 v196, v118, v119
	v_cvt_pk_bf16_f32 v197, v120, v121
	v_cvt_pk_bf16_f32 v198, v114, v115
	v_cvt_pk_bf16_f32 v199, v116, v117
	global_store_dwordx4 v155, v[196:199], s[26:27] offset:16
	v_mul_f32_e32 v200, v175, v174
	v_add_u32_e32 v155, 0x800, v201
	v_fma_f32 v188, -v200, v212, v213
	v_fma_f32 v189, -v200, v214, v215
	v_fma_f32 v190, -v200, v216, v217
	v_fma_f32 v191, -v200, v218, v219
	v_fma_f32 v192, -v200, v220, v221
	v_fma_f32 v193, -v200, v222, v223
	v_fma_f32 v194, -v200, v224, v225
	v_fma_f32 v195, -v200, v226, v227
	v_fma_f32 v110, v175, v110, v188
	v_fma_f32 v111, v175, v111, v189
	v_fma_f32 v112, v175, v112, v190
	v_fma_f32 v113, v175, v113, v191
	v_fma_f32 v106, v175, v106, v192
	v_fma_f32 v107, v175, v107, v193
	v_fma_f32 v108, v175, v108, v194
	v_fma_f32 v109, v175, v109, v195
	v_max_f32_e32 v110, 0, v110
	v_max_f32_e32 v111, 0, v111
	v_max_f32_e32 v112, 0, v112
	v_max_f32_e32 v113, 0, v113
	v_max_f32_e32 v106, 0, v106
	v_max_f32_e32 v107, 0, v107
	v_max_f32_e32 v108, 0, v108
	v_max_f32_e32 v109, 0, v109
	v_mul_f32_e32 v110, v110, v110
	v_mul_f32_e32 v111, v111, v111
	v_mul_f32_e32 v112, v112, v112
	v_mul_f32_e32 v113, v113, v113
	v_mul_f32_e32 v106, v106, v106
	v_mul_f32_e32 v107, v107, v107
	v_mul_f32_e32 v108, v108, v108
	v_mul_f32_e32 v109, v109, v109
	v_cvt_pk_bf16_f32 v196, v110, v111
	v_cvt_pk_bf16_f32 v197, v112, v113
	v_cvt_pk_bf16_f32 v198, v106, v107
	v_cvt_pk_bf16_f32 v199, v108, v109
	global_store_dwordx4 v155, v[196:199], s[26:27]
	v_fma_f32 v188, -v200, v228, v229
	v_fma_f32 v189, -v200, v230, v231
	v_fma_f32 v190, -v200, v232, v233
	v_fma_f32 v191, -v200, v234, v235
	v_fma_f32 v192, -v200, v236, v237
	v_fma_f32 v193, -v200, v238, v239
	v_fma_f32 v194, -v200, v240, v241
	v_fma_f32 v195, -v200, v242, v243
	v_fma_f32 v102, v175, v102, v188
	v_fma_f32 v103, v175, v103, v189
	v_fma_f32 v104, v175, v104, v190
	v_fma_f32 v105, v175, v105, v191
	v_fma_f32 v98, v175, v98, v192
	v_fma_f32 v99, v175, v99, v193
	v_fma_f32 v100, v175, v100, v194
	v_fma_f32 v101, v175, v101, v195
	v_max_f32_e32 v102, 0, v102
	v_max_f32_e32 v103, 0, v103
	v_max_f32_e32 v104, 0, v104
	v_max_f32_e32 v105, 0, v105
	v_max_f32_e32 v98, 0, v98
	v_max_f32_e32 v99, 0, v99
	v_max_f32_e32 v100, 0, v100
; __device__ __forceinline__ float bf_lo(unsigned w) { return __uint_as_float(w << 16); }
; __device__ __forceinline__ float bf_hi(unsigned w) { return __uint_as_float(w & 0xffff0000u); }
; __device__ __forceinline__ u32x4 pack8(const f32x4 a, const f32x4 b) { u32x4 w; w.x = cvt_pk_bf16(a[0], a[1]); w.y = cvt_pk_bf16(a[2], a[3]); w.z = cvt_pk_bf16(b[0], b[1]); w.w = cvt_pk_bf16(b[2], b[3]); return w; }
;     __device__ __forceinline__ void operator()(const f32x4 (&acc)[2][2][4][2], const pg8::Unit& u, int wr, int wc, int fr, int fq, LAS unsigned char* lds, int par) const {
;     ...
;                 const int row = row0 + ai * 128 + m * 16, lrow = ai * 128 + wr * 64 + m * 16 + fr;
;                 float mu = 0.f, rstd = 1.f; if (fold) { mu = rsb[2 * lrow]; rstd = rsb[2 * lrow + 1]; }
; #pragma unroll
;                 for (int bj = 0; bj < 2; ++bj) {
;                     const size_t off = (size_t)row * ld + c0 + bj * 8;
;                     f32x4 v0 = acc[ai][bj][m][0], v1 = acc[ai][bj][m][1];
;                     if (fold) fold_apply(v0, v1, mu, rstd, cvb, wc * 64 + 16 * fq + bj * 8);
;                     if (MODE == 0) { v0 *= scale; v1 *= scale; }
;                     if (MODE == 1) {
; #pragma unroll
;                         for (int j = 0; j < 4; ++j) { const float a = fmaxf(v0[j], 0.f), b = fmaxf(v1[j], 0.f); v0[j] = a * a; v1[j] = b * b; }
;                     }
;                     if (MODE == 2 || MODE == 3) {
;                         const u32x4 gw = *(const u32x4*)(gate + off);
;                         v0[0] *= bf_lo(gw.x); v0[1] *= bf_hi(gw.x); v0[2] *= bf_lo(gw.y); v0[3] *= bf_hi(gw.y);
;                         v1[0] *= bf_lo(gw.z); v1[1] *= bf_hi(gw.z); v1[2] *= bf_lo(gw.w); v1[3] *= bf_hi(gw.w);
;                     }
;                     if (MODE == 3) {
;                         const u32x4 pw = *(const u32x4*)(o + off);
;                         v0[0] += bf_lo(pw.x); v0[1] += bf_hi(pw.x); v0[2] += bf_lo(pw.y); v0[3] += bf_hi(pw.y);
;                         v1[0] += bf_lo(pw.z); v1[1] += bf_hi(pw.z); v1[2] += bf_lo(pw.w); v1[3] += bf_hi(pw.w);
;                     }
;                     *(u32x4*)(o + off) = pack8(v0, v1);
	v_max_f32_e32 v101, 0, v101
	v_mul_f32_e32 v102, v102, v102
	v_mul_f32_e32 v103, v103, v103
	v_mul_f32_e32 v104, v104, v104
	v_mul_f32_e32 v105, v105, v105
	v_mul_f32_e32 v98, v98, v98
	v_mul_f32_e32 v99, v99, v99
	v_mul_f32_e32 v100, v100, v100
	v_mul_f32_e32 v101, v101, v101
	v_cvt_pk_bf16_f32 v196, v102, v103
	v_cvt_pk_bf16_f32 v197, v104, v105
	v_cvt_pk_bf16_f32 v198, v98, v99
	v_cvt_pk_bf16_f32 v199, v100, v101
	global_store_dwordx4 v155, v[196:199], s[26:27] offset:16
	v_mul_f32_e32 v200, v177, v176
	v_add_u32_e32 v155, 0x1000, v201
	v_fma_f32 v188, -v200, v212, v213
	v_fma_f32 v189, -v200, v214, v215
	v_fma_f32 v190, -v200, v216, v217
	v_fma_f32 v191, -v200, v218, v219
	v_fma_f32 v192, -v200, v220, v221
	v_fma_f32 v193, -v200, v222, v223
	v_fma_f32 v194, -v200, v224, v225
	v_fma_f32 v195, -v200, v226, v227
	v_fma_f32 v94, v177, v94, v188
	v_fma_f32 v95, v177, v95, v189
	v_fma_f32 v96, v177, v96, v190
	v_fma_f32 v97, v177, v97, v191
	v_fma_f32 v90, v177, v90, v192
	v_fma_f32 v91, v177, v91, v193
	v_fma_f32 v92, v177, v92, v194
	v_fma_f32 v93, v177, v93, v195
	v_max_f32_e32 v94, 0, v94
	v_max_f32_e32 v95, 0, v95
	v_max_f32_e32 v96, 0, v96
	v_max_f32_e32 v97, 0, v97
	v_max_f32_e32 v90, 0, v90
	v_max_f32_e32 v91, 0, v91
	v_max_f32_e32 v92, 0, v92
	v_max_f32_e32 v93, 0, v93
	v_mul_f32_e32 v94, v94, v94
	v_mul_f32_e32 v95, v95, v95
	v_mul_f32_e32 v96, v96, v96
	v_mul_f32_e32 v97, v97, v97
	v_mul_f32_e32 v90, v90, v90
	v_mul_f32_e32 v91, v91, v91
	v_mul_f32_e32 v92, v92, v92
	v_mul_f32_e32 v93, v93, v93
	v_cvt_pk_bf16_f32 v196, v94, v95
	v_cvt_pk_bf16_f32 v197, v96, v97
	v_cvt_pk_bf16_f32 v198, v90, v91
	v_cvt_pk_bf16_f32 v199, v92, v93
	global_store_dwordx4 v155, v[196:199], s[26:27]
	v_fma_f32 v188, -v200, v228, v229
	v_fma_f32 v189, -v200, v230, v231
	v_fma_f32 v190, -v200, v232, v233
	v_fma_f32 v191, -v200, v234, v235
	v_fma_f32 v192, -v200, v236, v237
	v_fma_f32 v193, -v200, v238, v239
	v_fma_f32 v194, -v200, v240, v241
	v_fma_f32 v195, -v200, v242, v243
	v_fma_f32 v86, v177, v86, v188
	v_fma_f32 v87, v177, v87, v189
	v_fma_f32 v88, v177, v88, v190
	v_fma_f32 v89, v177, v89, v191
	v_fma_f32 v82, v177, v82, v192
	v_fma_f32 v83, v177, v83, v193
	v_fma_f32 v84, v177, v84, v194
	v_fma_f32 v85, v177, v85, v195
	v_max_f32_e32 v86, 0, v86
	v_max_f32_e32 v87, 0, v87
	v_max_f32_e32 v88, 0, v88
	v_max_f32_e32 v89, 0, v89
	v_max_f32_e32 v82, 0, v82
	v_max_f32_e32 v83, 0, v83
	v_max_f32_e32 v84, 0, v84
	v_max_f32_e32 v85, 0, v85
	v_mul_f32_e32 v86, v86, v86
	v_mul_f32_e32 v87, v87, v87
	v_mul_f32_e32 v88, v88, v88
	v_mul_f32_e32 v89, v89, v89
	v_mul_f32_e32 v82, v82, v82
	v_mul_f32_e32 v83, v83, v83
	v_mul_f32_e32 v84, v84, v84
	v_mul_f32_e32 v85, v85, v85
	v_cvt_pk_bf16_f32 v196, v86, v87
	v_cvt_pk_bf16_f32 v197, v88, v89
	v_cvt_pk_bf16_f32 v198, v82, v83
	v_cvt_pk_bf16_f32 v199, v84, v85
	global_store_dwordx4 v155, v[196:199], s[26:27] offset:16
	v_mul_f32_e32 v200, v179, v178
	v_add_u32_e32 v155, 0x1800, v201
	v_fma_f32 v188, -v200, v212, v213
	v_fma_f32 v189, -v200, v214, v215
	v_fma_f32 v190, -v200, v216, v217
	v_fma_f32 v191, -v200, v218, v219
	v_fma_f32 v192, -v200, v220, v221
	v_fma_f32 v193, -v200, v222, v223
	v_fma_f32 v194, -v200, v224, v225
	v_fma_f32 v195, -v200, v226, v227
	v_fma_f32 v78, v179, v78, v188
	v_fma_f32 v79, v179, v79, v189
	v_fma_f32 v80, v179, v80, v190
	v_fma_f32 v81, v179, v81, v191
	v_fma_f32 v74, v179, v74, v192
	v_fma_f32 v75, v179, v75, v193
	v_fma_f32 v76, v179, v76, v194
	v_fma_f32 v77, v179, v77, v195
	v_max_f32_e32 v78, 0, v78
	v_max_f32_e32 v79, 0, v79
	v_max_f32_e32 v80, 0, v80
	v_max_f32_e32 v81, 0, v81
	v_max_f32_e32 v74, 0, v74
	v_max_f32_e32 v75, 0, v75
	v_max_f32_e32 v76, 0, v76
	v_max_f32_e32 v77, 0, v77
	v_mul_f32_e32 v78, v78, v78
	v_mul_f32_e32 v79, v79, v79
	v_mul_f32_e32 v80, v80, v80
	v_mul_f32_e32 v81, v81, v81
	v_mul_f32_e32 v74, v74, v74
	v_mul_f32_e32 v75, v75, v75
	v_mul_f32_e32 v76, v76, v76
	v_mul_f32_e32 v77, v77, v77
	v_cvt_pk_bf16_f32 v196, v78, v79
	v_cvt_pk_bf16_f32 v197, v80, v81
	v_cvt_pk_bf16_f32 v198, v74, v75
	v_cvt_pk_bf16_f32 v199, v76, v77
	global_store_dwordx4 v155, v[196:199], s[26:27]
	v_fma_f32 v188, -v200, v228, v229
	v_fma_f32 v189, -v200, v230, v231
	v_fma_f32 v190, -v200, v232, v233
	v_fma_f32 v191, -v200, v234, v235
	v_fma_f32 v192, -v200, v236, v237
	v_fma_f32 v193, -v200, v238, v239
	v_fma_f32 v194, -v200, v240, v241
	v_fma_f32 v195, -v200, v242, v243
	v_fma_f32 v70, v179, v70, v188
	v_fma_f32 v71, v179, v71, v189
	v_fma_f32 v72, v179, v72, v190
	v_fma_f32 v73, v179, v73, v191
	v_fma_f32 v66, v179, v66, v192
	v_fma_f32 v67, v179, v67, v193
	v_fma_f32 v68, v179, v68, v194
	v_fma_f32 v69, v179, v69, v195
	v_max_f32_e32 v70, 0, v70
	v_max_f32_e32 v71, 0, v71
	v_max_f32_e32 v72, 0, v72
	v_max_f32_e32 v73, 0, v73
	v_max_f32_e32 v66, 0, v66
	v_max_f32_e32 v67, 0, v67
	v_max_f32_e32 v68, 0, v68
	v_max_f32_e32 v69, 0, v69
	v_mul_f32_e32 v70, v70, v70
	v_mul_f32_e32 v71, v71, v71
	v_mul_f32_e32 v72, v72, v72
	v_mul_f32_e32 v73, v73, v73
	v_mul_f32_e32 v66, v66, v66
	v_mul_f32_e32 v67, v67, v67
	v_mul_f32_e32 v68, v68, v68
	v_mul_f32_e32 v69, v69, v69
	v_cvt_pk_bf16_f32 v196, v70, v71
	v_cvt_pk_bf16_f32 v197, v72, v73
	v_cvt_pk_bf16_f32 v198, v66, v67
	v_cvt_pk_bf16_f32 v199, v68, v69
	global_store_dwordx4 v155, v[196:199], s[26:27] offset:16
	v_mul_f32_e32 v200, v181, v180
	v_add_u32_e32 v155, 0x4000, v201
	v_fma_f32 v188, -v200, v212, v213
	v_fma_f32 v189, -v200, v214, v215
	v_fma_f32 v190, -v200, v216, v217
	v_fma_f32 v191, -v200, v218, v219
	v_fma_f32 v192, -v200, v220, v221
	v_fma_f32 v193, -v200, v222, v223
	v_fma_f32 v194, -v200, v224, v225
	v_fma_f32 v195, -v200, v226, v227
; __device__ __forceinline__ float bf_lo(unsigned w) { return __uint_as_float(w << 16); }
; __device__ __forceinline__ float bf_hi(unsigned w) { return __uint_as_float(w & 0xffff0000u); }
; __device__ __forceinline__ u32x4 pack8(const f32x4 a, const f32x4 b) { u32x4 w; w.x = cvt_pk_bf16(a[0], a[1]); w.y = cvt_pk_bf16(a[2], a[3]); w.z = cvt_pk_bf16(b[0], b[1]); w.w = cvt_pk_bf16(b[2], b[3]); return w; }
;     __device__ __forceinline__ void operator()(const f32x4 (&acc)[2][2][4][2], const pg8::Unit& u, int wr, int wc, int fr, int fq, LAS unsigned char* lds, int par) const {
;     ...
;                 const int row = row0 + ai * 128 + m * 16, lrow = ai * 128 + wr * 64 + m * 16 + fr;
;                 float mu = 0.f, rstd = 1.f; if (fold) { mu = rsb[2 * lrow]; rstd = rsb[2 * lrow + 1]; }
; #pragma unroll
;                 for (int bj = 0; bj < 2; ++bj) {
;                     const size_t off = (size_t)row * ld + c0 + bj * 8;
;                     f32x4 v0 = acc[ai][bj][m][0], v1 = acc[ai][bj][m][1];
;                     if (fold) fold_apply(v0, v1, mu, rstd, cvb, wc * 64 + 16 * fq + bj * 8);
;                     if (MODE == 0) { v0 *= scale; v1 *= scale; }
;                     if (MODE == 1) {
; #pragma unroll
;                         for (int j = 0; j < 4; ++j) { const float a = fmaxf(v0[j], 0.f), b = fmaxf(v1[j], 0.f); v0[j] = a * a; v1[j] = b * b; }
;                     }
;                     if (MODE == 2 || MODE == 3) {
;                         const u32x4 gw = *(const u32x4*)(gate + off);
;                         v0[0] *= bf_lo(gw.x); v0[1] *= bf_hi(gw.x); v0[2] *= bf_lo(gw.y); v0[3] *= bf_hi(gw.y);
;                         v1[0] *= bf_lo(gw.z); v1[1] *= bf_hi(gw.z); v1[2] *= bf_lo(gw.w); v1[3] *= bf_hi(gw.w);
;                     }
;                     if (MODE == 3) {
;                         const u32x4 pw = *(const u32x4*)(o + off);
;                         v0[0] += bf_lo(pw.x); v0[1] += bf_hi(pw.x); v0[2] += bf_lo(pw.y); v0[3] += bf_hi(pw.y);
;                         v1[0] += bf_lo(pw.z); v1[1] += bf_hi(pw.z); v1[2] += bf_lo(pw.w); v1[3] += bf_hi(pw.w);
;                     }
;                     *(u32x4*)(o + off) = pack8(v0, v1);
	v_fma_f32 v62, v181, v62, v188
	v_fma_f32 v63, v181, v63, v189
	v_fma_f32 v64, v181, v64, v190
	v_fma_f32 v65, v181, v65, v191
	v_fma_f32 v58, v181, v58, v192
	v_fma_f32 v59, v181, v59, v193
	v_fma_f32 v60, v181, v60, v194
	v_fma_f32 v61, v181, v61, v195
	v_max_f32_e32 v62, 0, v62
	v_max_f32_e32 v63, 0, v63
	v_max_f32_e32 v64, 0, v64
	v_max_f32_e32 v65, 0, v65
	v_max_f32_e32 v58, 0, v58
	v_max_f32_e32 v59, 0, v59
	v_max_f32_e32 v60, 0, v60
	v_max_f32_e32 v61, 0, v61
	v_mul_f32_e32 v62, v62, v62
	v_mul_f32_e32 v63, v63, v63
	v_mul_f32_e32 v64, v64, v64
	v_mul_f32_e32 v65, v65, v65
	v_mul_f32_e32 v58, v58, v58
	v_mul_f32_e32 v59, v59, v59
	v_mul_f32_e32 v60, v60, v60
	v_mul_f32_e32 v61, v61, v61
	v_cvt_pk_bf16_f32 v196, v62, v63
	v_cvt_pk_bf16_f32 v197, v64, v65
	v_cvt_pk_bf16_f32 v198, v58, v59
	v_cvt_pk_bf16_f32 v199, v60, v61
	global_store_dwordx4 v155, v[196:199], s[26:27]
	v_fma_f32 v188, -v200, v228, v229
	v_fma_f32 v189, -v200, v230, v231
	v_fma_f32 v190, -v200, v232, v233
	v_fma_f32 v191, -v200, v234, v235
	v_fma_f32 v192, -v200, v236, v237
	v_fma_f32 v193, -v200, v238, v239
	v_fma_f32 v194, -v200, v240, v241
	v_fma_f32 v195, -v200, v242, v243
	v_fma_f32 v54, v181, v54, v188
	v_fma_f32 v55, v181, v55, v189
	v_fma_f32 v56, v181, v56, v190
	v_fma_f32 v57, v181, v57, v191
	v_fma_f32 v50, v181, v50, v192
	v_fma_f32 v51, v181, v51, v193
	v_fma_f32 v52, v181, v52, v194
	v_fma_f32 v53, v181, v53, v195
	v_max_f32_e32 v54, 0, v54
	v_max_f32_e32 v55, 0, v55
	v_max_f32_e32 v56, 0, v56
	v_max_f32_e32 v57, 0, v57
	v_max_f32_e32 v50, 0, v50
	v_max_f32_e32 v51, 0, v51
	v_max_f32_e32 v52, 0, v52
	v_max_f32_e32 v53, 0, v53
	v_mul_f32_e32 v54, v54, v54
	v_mul_f32_e32 v55, v55, v55
	v_mul_f32_e32 v56, v56, v56
	v_mul_f32_e32 v57, v57, v57
	v_mul_f32_e32 v50, v50, v50
	v_mul_f32_e32 v51, v51, v51
	v_mul_f32_e32 v52, v52, v52
	v_mul_f32_e32 v53, v53, v53
	v_cvt_pk_bf16_f32 v196, v54, v55
	v_cvt_pk_bf16_f32 v197, v56, v57
	v_cvt_pk_bf16_f32 v198, v50, v51
	v_cvt_pk_bf16_f32 v199, v52, v53
	global_store_dwordx4 v155, v[196:199], s[26:27] offset:16
	v_mul_f32_e32 v200, v183, v182
	v_add_u32_e32 v155, 0x4800, v201
	v_fma_f32 v188, -v200, v212, v213
	v_fma_f32 v189, -v200, v214, v215
	v_fma_f32 v190, -v200, v216, v217
	v_fma_f32 v191, -v200, v218, v219
	v_fma_f32 v192, -v200, v220, v221
	v_fma_f32 v193, -v200, v222, v223
	v_fma_f32 v194, -v200, v224, v225
	v_fma_f32 v195, -v200, v226, v227
	v_fma_f32 v46, v183, v46, v188
	v_fma_f32 v47, v183, v47, v189
	v_fma_f32 v48, v183, v48, v190
	v_fma_f32 v49, v183, v49, v191
	v_fma_f32 v42, v183, v42, v192
	v_fma_f32 v43, v183, v43, v193
	v_fma_f32 v44, v183, v44, v194
	v_fma_f32 v45, v183, v45, v195
	v_max_f32_e32 v46, 0, v46
	v_max_f32_e32 v47, 0, v47
	v_max_f32_e32 v48, 0, v48
	v_max_f32_e32 v49, 0, v49
	v_max_f32_e32 v42, 0, v42
	v_max_f32_e32 v43, 0, v43
	v_max_f32_e32 v44, 0, v44
	v_max_f32_e32 v45, 0, v45
	v_mul_f32_e32 v46, v46, v46
	v_mul_f32_e32 v47, v47, v47
	v_mul_f32_e32 v48, v48, v48
	v_mul_f32_e32 v49, v49, v49
	v_mul_f32_e32 v42, v42, v42
	v_mul_f32_e32 v43, v43, v43
	v_mul_f32_e32 v44, v44, v44
	v_mul_f32_e32 v45, v45, v45
	v_cvt_pk_bf16_f32 v196, v46, v47
	v_cvt_pk_bf16_f32 v197, v48, v49
	v_cvt_pk_bf16_f32 v198, v42, v43
	v_cvt_pk_bf16_f32 v199, v44, v45
	global_store_dwordx4 v155, v[196:199], s[26:27]
	v_fma_f32 v188, -v200, v228, v229
	v_fma_f32 v189, -v200, v230, v231
	v_fma_f32 v190, -v200, v232, v233
	v_fma_f32 v191, -v200, v234, v235
	v_fma_f32 v192, -v200, v236, v237
	v_fma_f32 v193, -v200, v238, v239
	v_fma_f32 v194, -v200, v240, v241
	v_fma_f32 v195, -v200, v242, v243
	v_fma_f32 v38, v183, v38, v188
	v_fma_f32 v39, v183, v39, v189
	v_fma_f32 v40, v183, v40, v190
	v_fma_f32 v41, v183, v41, v191
	v_fma_f32 v34, v183, v34, v192
	v_fma_f32 v35, v183, v35, v193
	v_fma_f32 v36, v183, v36, v194
	v_fma_f32 v37, v183, v37, v195
	v_max_f32_e32 v38, 0, v38
	v_max_f32_e32 v39, 0, v39
	v_max_f32_e32 v40, 0, v40
	v_max_f32_e32 v41, 0, v41
	v_max_f32_e32 v34, 0, v34
	v_max_f32_e32 v35, 0, v35
	v_max_f32_e32 v36, 0, v36
	v_max_f32_e32 v37, 0, v37
	v_mul_f32_e32 v38, v38, v38
	v_mul_f32_e32 v39, v39, v39
	v_mul_f32_e32 v40, v40, v40
	v_mul_f32_e32 v41, v41, v41
	v_mul_f32_e32 v34, v34, v34
	v_mul_f32_e32 v35, v35, v35
	v_mul_f32_e32 v36, v36, v36
	v_mul_f32_e32 v37, v37, v37
	v_cvt_pk_bf16_f32 v196, v38, v39
	v_cvt_pk_bf16_f32 v197, v40, v41
	v_cvt_pk_bf16_f32 v198, v34, v35
	v_cvt_pk_bf16_f32 v199, v36, v37
	global_store_dwordx4 v155, v[196:199], s[26:27] offset:16
	v_mul_f32_e32 v200, v185, v184
	v_add_u32_e32 v155, 0x5000, v201
	v_fma_f32 v188, -v200, v212, v213
	v_fma_f32 v189, -v200, v214, v215
	v_fma_f32 v190, -v200, v216, v217
	v_fma_f32 v191, -v200, v218, v219
	v_fma_f32 v192, -v200, v220, v221
	v_fma_f32 v193, -v200, v222, v223
	v_fma_f32 v194, -v200, v224, v225
	v_fma_f32 v195, -v200, v226, v227
	v_fma_f32 v30, v185, v30, v188
	v_fma_f32 v31, v185, v31, v189
	v_fma_f32 v32, v185, v32, v190
	v_fma_f32 v33, v185, v33, v191
	v_fma_f32 v26, v185, v26, v192
	v_fma_f32 v27, v185, v27, v193
	v_fma_f32 v28, v185, v28, v194
	v_fma_f32 v29, v185, v29, v195
	v_max_f32_e32 v30, 0, v30
	v_max_f32_e32 v31, 0, v31
	v_max_f32_e32 v32, 0, v32
	v_max_f32_e32 v33, 0, v33
	v_max_f32_e32 v26, 0, v26
	v_max_f32_e32 v27, 0, v27
	v_max_f32_e32 v28, 0, v28
	v_max_f32_e32 v29, 0, v29
	v_mul_f32_e32 v30, v30, v30
	v_mul_f32_e32 v31, v31, v31
	v_mul_f32_e32 v32, v32, v32
	v_mul_f32_e32 v33, v33, v33
	v_mul_f32_e32 v26, v26, v26
	v_mul_f32_e32 v27, v27, v27
	v_mul_f32_e32 v28, v28, v28
	v_mul_f32_e32 v29, v29, v29
	v_cvt_pk_bf16_f32 v196, v30, v31
	v_cvt_pk_bf16_f32 v197, v32, v33
	v_cvt_pk_bf16_f32 v198, v26, v27
;     __device__ __forceinline__ void prepare(const pg8::Unit& u, LAS unsigned char* lds, int par, int tid) const {
;         if (stats == nullptr) return;
;         const int h = tid >> 8, tt = tid & 255, rl = tt >> 1, part = tt & 1, lrow = (rl >> 6) * 128 + h * 64 + (rl & 63);
;         const float* sp = stats + ((size_t)(u.pm * 256 + lrow) * 32 + part * 16) * 2;
;         float s1 = 0.f, s2 = 0.f;
; #pragma unroll
;         for (int i = 0; i < 8; ++i) { const f32x4 v = *(const f32x4*)(sp + 4 * i); s1 += v[0] + v[2]; s2 += v[1] + v[3]; }
;         s1 += shflx(s1, 1, tid & 63); s2 += shflx(s2, 1, tid & 63);
;     __device__ __forceinline__ void operator()(const f32x4 (&acc)[2][2][4][2], const pg8::Unit& u, int wr, int wc, int fr, int fq, LAS unsigned char* lds, int par) const {
;     ...
;                 const int row = row0 + ai * 128 + m * 16, lrow = ai * 128 + wr * 64 + m * 16 + fr;
;                 float mu = 0.f, rstd = 1.f; if (fold) { mu = rsb[2 * lrow]; rstd = rsb[2 * lrow + 1]; }
; #pragma unroll
;                 for (int bj = 0; bj < 2; ++bj) {
;                     const size_t off = (size_t)row * ld + c0 + bj * 8;
;                     f32x4 v0 = acc[ai][bj][m][0], v1 = acc[ai][bj][m][1];
;                     if (fold) fold_apply(v0, v1, mu, rstd, cvb, wc * 64 + 16 * fq + bj * 8);
;                     if (MODE == 0) { v0 *= scale; v1 *= scale; }
;                     if (MODE == 1) {
; #pragma unroll
;                         for (int j = 0; j < 4; ++j) { const float a = fmaxf(v0[j], 0.f), b = fmaxf(v1[j], 0.f); v0[j] = a * a; v1[j] = b * b; }
;                     }
;                     if (MODE == 2 || MODE == 3) {
;                         const u32x4 gw = *(const u32x4*)(gate + off);
;                         v0[0] *= bf_lo(gw.x); v0[1] *= bf_hi(gw.x); v0[2] *= bf_lo(gw.y); v0[3] *= bf_hi(gw.y);
;                         v1[0] *= bf_lo(gw.z); v1[1] *= bf_hi(gw.z); v1[2] *= bf_lo(gw.w); v1[3] *= bf_hi(gw.w);
;                     }
;                     if (MODE == 3) {
;                         const u32x4 pw = *(const u32x4*)(o + off);
;                         v0[0] += bf_lo(pw.x); v0[1] += bf_hi(pw.x); v0[2] += bf_lo(pw.y); v0[3] += bf_hi(pw.y);
;                         v1[0] += bf_lo(pw.z); v1[1] += bf_hi(pw.z); v1[2] += bf_lo(pw.w); v1[3] += bf_hi(pw.w);
;                     }
;                     *(u32x4*)(o + off) = pack8(v0, v1);
	v_cvt_pk_bf16_f32 v199, v28, v29
	global_store_dwordx4 v155, v[196:199], s[26:27]
	v_fma_f32 v188, -v200, v228, v229
	v_fma_f32 v189, -v200, v230, v231
	v_fma_f32 v190, -v200, v232, v233
	v_fma_f32 v191, -v200, v234, v235
	v_fma_f32 v192, -v200, v236, v237
	v_fma_f32 v193, -v200, v238, v239
	v_fma_f32 v194, -v200, v240, v241
	v_fma_f32 v195, -v200, v242, v243
	v_fma_f32 v22, v185, v22, v188
	v_fma_f32 v23, v185, v23, v189
	v_fma_f32 v24, v185, v24, v190
	v_fma_f32 v25, v185, v25, v191
	v_fma_f32 v18, v185, v18, v192
	v_fma_f32 v19, v185, v19, v193
	v_fma_f32 v20, v185, v20, v194
	v_fma_f32 v21, v185, v21, v195
	v_max_f32_e32 v22, 0, v22
	v_max_f32_e32 v23, 0, v23
	v_max_f32_e32 v24, 0, v24
	v_max_f32_e32 v25, 0, v25
	v_max_f32_e32 v18, 0, v18
	v_max_f32_e32 v19, 0, v19
	v_max_f32_e32 v20, 0, v20
	v_max_f32_e32 v21, 0, v21
	v_mul_f32_e32 v22, v22, v22
	v_mul_f32_e32 v23, v23, v23
	v_mul_f32_e32 v24, v24, v24
	v_mul_f32_e32 v25, v25, v25
	v_mul_f32_e32 v18, v18, v18
	v_mul_f32_e32 v19, v19, v19
	v_mul_f32_e32 v20, v20, v20
	v_mul_f32_e32 v21, v21, v21
	v_cvt_pk_bf16_f32 v196, v22, v23
	v_cvt_pk_bf16_f32 v197, v24, v25
	v_cvt_pk_bf16_f32 v198, v18, v19
	v_cvt_pk_bf16_f32 v199, v20, v21
	global_store_dwordx4 v155, v[196:199], s[26:27] offset:16
	v_mul_f32_e32 v200, v187, v186
	v_add_u32_e32 v155, 0x5800, v201
	v_fma_f32 v188, -v200, v212, v213
	v_fma_f32 v189, -v200, v214, v215
	v_fma_f32 v190, -v200, v216, v217
	v_fma_f32 v191, -v200, v218, v219
	v_fma_f32 v192, -v200, v220, v221
	v_fma_f32 v193, -v200, v222, v223
	v_fma_f32 v194, -v200, v224, v225
	v_fma_f32 v195, -v200, v226, v227
	v_fma_f32 v14, v187, v14, v188
	v_fma_f32 v15, v187, v15, v189
	v_fma_f32 v16, v187, v16, v190
	v_fma_f32 v17, v187, v17, v191
	v_fma_f32 v10, v187, v10, v192
	v_fma_f32 v11, v187, v11, v193
	v_fma_f32 v12, v187, v12, v194
	v_fma_f32 v13, v187, v13, v195
	v_max_f32_e32 v14, 0, v14
	v_max_f32_e32 v15, 0, v15
	v_max_f32_e32 v16, 0, v16
	v_max_f32_e32 v17, 0, v17
	v_max_f32_e32 v10, 0, v10
	v_max_f32_e32 v11, 0, v11
	v_max_f32_e32 v12, 0, v12
	v_max_f32_e32 v13, 0, v13
	v_mul_f32_e32 v14, v14, v14
	v_mul_f32_e32 v15, v15, v15
	v_mul_f32_e32 v16, v16, v16
	v_mul_f32_e32 v17, v17, v17
	v_mul_f32_e32 v10, v10, v10
	v_mul_f32_e32 v11, v11, v11
	v_mul_f32_e32 v12, v12, v12
	v_mul_f32_e32 v13, v13, v13
	v_cvt_pk_bf16_f32 v196, v14, v15
	v_cvt_pk_bf16_f32 v197, v16, v17
	v_cvt_pk_bf16_f32 v198, v10, v11
	v_cvt_pk_bf16_f32 v199, v12, v13
	global_store_dwordx4 v155, v[196:199], s[26:27]
	v_fma_f32 v188, -v200, v228, v229
	v_fma_f32 v189, -v200, v230, v231
	v_fma_f32 v190, -v200, v232, v233
	v_fma_f32 v191, -v200, v234, v235
	v_fma_f32 v192, -v200, v236, v237
	v_fma_f32 v193, -v200, v238, v239
	v_fma_f32 v194, -v200, v240, v241
	v_fma_f32 v195, -v200, v242, v243
	v_fma_f32 v6, v187, v6, v188
	v_fma_f32 v7, v187, v7, v189
	v_fma_f32 v8, v187, v8, v190
	v_fma_f32 v9, v187, v9, v191
	v_fma_f32 v2, v187, v2, v192
	v_fma_f32 v3, v187, v3, v193
	v_fma_f32 v4, v187, v4, v194
	v_fma_f32 v5, v187, v5, v195
	v_max_f32_e32 v6, 0, v6
	v_max_f32_e32 v7, 0, v7
	v_max_f32_e32 v8, 0, v8
	v_max_f32_e32 v9, 0, v9
	v_max_f32_e32 v2, 0, v2
	v_max_f32_e32 v3, 0, v3
	v_max_f32_e32 v4, 0, v4
	v_max_f32_e32 v5, 0, v5
	v_mul_f32_e32 v6, v6, v6
	v_mul_f32_e32 v7, v7, v7
	v_mul_f32_e32 v8, v8, v8
	v_mul_f32_e32 v9, v9, v9
	v_mul_f32_e32 v2, v2, v2
	v_mul_f32_e32 v3, v3, v3
	v_mul_f32_e32 v4, v4, v4
	v_mul_f32_e32 v5, v5, v5
	v_cvt_pk_bf16_f32 v196, v6, v7
	v_cvt_pk_bf16_f32 v197, v8, v9
	v_cvt_pk_bf16_f32 v198, v2, v3
	v_cvt_pk_bf16_f32 v199, v4, v5
	global_store_dwordx4 v155, v[196:199], s[26:27] offset:16
	s_andn2_b64 vcc, exec, s[22:23]
	s_mov_b64 s[22:23], -1
	s_cbranch_vccnz .LBB0_164
	s_nop 0
	v_lshl_add_u32 v2, s16, 8, v144
	v_ashrrev_i32_e32 v3, 31, v2
	v_lshlrev_b64 v[2:3], 8, v[2:3]
	v_lshl_add_u64 v[6:7], v[136:137], 0, v[2:3]
	global_load_dwordx4 v[2:5], v[6:7], off
	global_load_dwordx4 v[222:225], v[6:7], off offset:16
	global_load_dwordx4 v[226:229], v[6:7], off offset:32
	global_load_dwordx4 v[230:233], v[6:7], off offset:48
	global_load_dwordx4 v[234:237], v[6:7], off offset:64
	global_load_dwordx4 v[238:241], v[6:7], off offset:80
	global_load_dwordx4 v[242:245], v[6:7], off offset:96
	global_load_dwordx4 v[246:249], v[6:7], off offset:112
	s_and_b32 s15, s39, 1
	s_waitcnt vmcnt(0) lgkmcnt(0)
	v_add_f32_e32 v2, v2, v4
	v_add_f32_e32 v8, 0, v2
	v_add_f32_e32 v2, v3, v5
	v_add_f32_e32 v9, 0, v2
	v_add_f32_e32 v2, v222, v224
	v_add_f32_e32 v8, v8, v2
	v_add_f32_e32 v2, v223, v225
	v_add_f32_e32 v9, v9, v2
	v_add_f32_e32 v2, v226, v228
	v_add_f32_e32 v8, v8, v2
	v_add_f32_e32 v2, v227, v229
	v_add_f32_e32 v9, v9, v2
	v_add_f32_e32 v2, v230, v232
	v_add_f32_e32 v8, v8, v2
	v_add_f32_e32 v2, v231, v233
	v_add_f32_e32 v9, v9, v2
	v_add_f32_e32 v2, v234, v236
	v_add_f32_e32 v8, v8, v2
	v_add_f32_e32 v2, v235, v237
	v_add_f32_e32 v9, v9, v2
	v_add_f32_e32 v2, v238, v240
	v_add_f32_e32 v8, v8, v2
	v_add_f32_e32 v2, v239, v241
	v_add_f32_e32 v9, v9, v2
	v_add_f32_e32 v2, v242, v244
	v_add_f32_e32 v8, v8, v2
	v_add_f32_e32 v2, v243, v245
	v_add_f32_e32 v9, v9, v2
	v_add_f32_e32 v2, v246, v248
	v_add_f32_e32 v3, v247, v249
	v_add_f32_e32 v2, v8, v2
	v_add_f32_e32 v3, v9, v3
	ds_bpermute_b32 v4, v145, v2
	ds_bpermute_b32 v5, v145, v3
	s_and_saveexec_b64 s[22:23], s[0:1]
	s_cbranch_execz .LBB0_179
	s_waitcnt lgkmcnt(1)
	v_add_f32_e32 v2, v2, v4
	v_mul_f32_e32 v2, 0x3a000000, v2
	s_waitcnt lgkmcnt(0)
	v_add_f32_e32 v3, v3, v5
	v_mul_f32_e32 v4, v2, v2
	v_fma_f32 v3, v3, s61, -v4
	v_add_f32_e32 v3, 0x3727c5ac, v3
	v_rsq_f32_e32 v3, v3
	v_lshl_add_u32 v4, s15, 11, v151
	ds_write_b64 v4, v[2:3]
